# v27 + mid-segment s_setprio 0/1 pairs removed from the 24 MFMA segments
# baseline (speedup 1.0000x reference)
; #define PG8_STAGE(bufoff, gbase, voff) do { _Pragma("unroll") for (int _i = 0; _i < 2; ++_i) \
;         __builtin_amdgcn_global_load_lds((const unsigned*)((const char*)(gbase) + (voff)[_i]), (PG8_LAS unsigned*)(lds + (bufoff) + ldsw + _i * 8192), 16, 0, 0); } while (0)
; #define PG8_LDA(dst, b, h) do { _Pragma("unroll") for (int m = 0; m < 4; ++m) _Pragma("unroll") for (int k = 0; k < 2; ++k) dst[m][k] = *(const PG8_LAS bf16x8*)(lds + PG8_SA(b, h) + aoff + m * 2048 + k * 1024); } while (0)
; #define PG8_LDB(dst, b, h) do { _Pragma("unroll") for (int n = 0; n < 2; ++n) _Pragma("unroll") for (int k = 0; k < 2; ++k) dst[n][k] = *(const PG8_LAS bf16x8*)(lds + PG8_SB(b, h) + boff + n * 2048 + k * 1024); } while (0)
; #define PG8_MMA(ai, bj, At, Bt) do { __builtin_amdgcn_s_setprio(1); _Pragma("unroll") for (int m = 0; m < 4; ++m) _Pragma("unroll") for (int n = 0; n < 2; ++n) _Pragma("unroll") for (int k = 0; k < 2; ++k) \
;         acc[ai][bj][m][n] = __builtin_amdgcn_mfma_f32_16x16x32_bf16(Bt[n][k], At[m][k], acc[ai][bj][m][n], 0, 0, 0); __builtin_amdgcn_s_setprio(0); } while (0)
; #define PG8_WAIT_V(n) asm volatile("s_waitcnt vmcnt(" #n ")" ::: "memory")
; #define PG8_WAIT_L(n) asm volatile("s_waitcnt lgkmcnt(" #n ")" ::: "memory")
; template <class Epi, class Sched, bool ALIGN_EPI = false, bool SP2 = false>
; __device__ __forceinline__ void gemm_phase(PG8_LAS unsigned char* lds, const Gemm g, const Sched& S, const Epi& E) {
;     ...
;             const bool last = (t == nt - 2);
;             const char* a1 = cA + (size_t)(t + 1) * kstep;
;             const char* a2 = last ? nA : cA + (size_t)(t + 2) * kstep; const char* b2 = last ? nB : cB + (size_t)(t + 2) * kstep;
;             const char* a3 = a2 + kstep; const char* b3 = b2 + kstep;
;             if (last && has_next) S.a_ready(nxt);
;             if constexpr (SP2) {
;             PG8_LDB(B0, 0, 0); PG8_LDB(B1, 0, 1); PG8_SCHED; PG8_LDA(At, 0, 0); PG8_STAGE(PG8_SA(1, 1), a1 + hstep, voffA);
;             PG8_WAIT_V(8); PG8_WAIT_L(0); PG8_BAR; PG8_MMA(0, 0, At, B0); PG8_MMA(0, 1, At, B1); PG8_BAR; PG8_SCHED;
;             PG8_LDA(At, 0, 1); PG8_STAGE(PG8_SB(0, 0), b2, voffB); PG8_STAGE(PG8_SB(0, 1), b2 + hstep, voffB); PG8_STAGE(PG8_SA(0, 0), a2, voffA);
;             PG8_WAIT_V(8); PG8_WAIT_L(0); PG8_BAR; PG8_MMA(1, 0, At, B0); PG8_MMA(1, 1, At, B1); PG8_BAR; PG8_SCHED;
.LBB0_146:
	s_add_u32 s44, s24, 0xfff80080
	s_addc_u32 s45, s25, -1
	s_add_i32 s55, 0, 0x10000
	s_cmp_eq_u32 s54, 28
	s_cselect_b32 s47, s21, s45
	s_cselect_b32 s46, s48, s44
	v_add_u32_e32 v167, s55, v147
	s_cselect_b32 s45, s19, s51
	s_cselect_b32 s44, s49, s50
	s_add_i32 s62, 0, 0x14000
	ds_read_b128 v[142:145], v167
	ds_read_b128 v[168:171], v167 offset:1024
	ds_read_b128 v[172:175], v167 offset:2048
	ds_read_b128 v[176:179], v167 offset:3072
	v_add_u32_e32 v167, s62, v147
	ds_read_b128 v[180:183], v167
	ds_read_b128 v[184:187], v167 offset:1024
	ds_read_b128 v[188:191], v167 offset:2048
	ds_read_b128 v[204:207], v167 offset:3072
	v_lshl_add_u64 v[192:193], s[24:25], 0, v[138:139]
	s_add_i32 m0, s1, 0xc000
	ds_read_b128 v[216:219], v166
	ds_read_b128 v[220:223], v166 offset:1024
	ds_read_b128 v[224:227], v166 offset:2048
	ds_read_b128 v[228:231], v166 offset:3072
	ds_read_b128 v[232:235], v166 offset:4096
	ds_read_b128 v[236:239], v166 offset:5120
	ds_read_b128 v[240:243], v166 offset:6144
	ds_read_b128 v[244:247], v166 offset:7168
	global_load_lds_dwordx4 v[192:193], off
	v_lshl_add_u64 v[192:193], s[24:25], 0, v[140:141]
	s_add_i32 m0, s1, 0xe000
	s_nop 0
	global_load_lds_dwordx4 v[192:193], off
	s_waitcnt vmcnt(8)
	s_waitcnt lgkmcnt(0)
	s_setprio 1
	s_barrier
	v_mfma_f32_16x16x32_bf16 v[126:129], v[142:145], v[216:219], v[126:129]
	v_mfma_f32_16x16x32_bf16 v[122:125], v[172:175], v[216:219], v[122:125]
	v_mfma_f32_16x16x32_bf16 v[114:117], v[142:145], v[224:227], v[114:117]
	v_mfma_f32_16x16x32_bf16 v[106:109], v[172:175], v[224:227], v[106:109]
	v_mfma_f32_16x16x32_bf16 v[98:101], v[142:145], v[232:235], v[98:101]
	v_mfma_f32_16x16x32_bf16 v[90:93], v[172:175], v[232:235], v[90:93]
	v_mfma_f32_16x16x32_bf16 v[82:85], v[142:145], v[240:243], v[82:85]
	v_mfma_f32_16x16x32_bf16 v[74:77], v[172:175], v[240:243], v[74:77]
	v_mfma_f32_16x16x32_bf16 v[126:129], v[168:171], v[220:223], v[126:129]
	v_mfma_f32_16x16x32_bf16 v[122:125], v[176:179], v[220:223], v[122:125]
	v_mfma_f32_16x16x32_bf16 v[114:117], v[168:171], v[228:231], v[114:117]
	v_mfma_f32_16x16x32_bf16 v[106:109], v[176:179], v[228:231], v[106:109]
	v_mfma_f32_16x16x32_bf16 v[98:101], v[168:171], v[236:239], v[98:101]
	v_mfma_f32_16x16x32_bf16 v[90:93], v[176:179], v[236:239], v[90:93]
	v_mfma_f32_16x16x32_bf16 v[82:85], v[168:171], v[244:247], v[82:85]
	v_mfma_f32_16x16x32_bf16 v[74:77], v[176:179], v[244:247], v[74:77]
	v_mfma_f32_16x16x32_bf16 v[118:121], v[180:183], v[216:219], v[118:121]
	v_mfma_f32_16x16x32_bf16 v[110:113], v[188:191], v[216:219], v[110:113]
	v_mfma_f32_16x16x32_bf16 v[102:105], v[180:183], v[224:227], v[102:105]
	v_mfma_f32_16x16x32_bf16 v[94:97], v[188:191], v[224:227], v[94:97]
	v_mfma_f32_16x16x32_bf16 v[86:89], v[180:183], v[232:235], v[86:89]
	v_mfma_f32_16x16x32_bf16 v[78:81], v[188:191], v[232:235], v[78:81]
	v_mfma_f32_16x16x32_bf16 v[70:73], v[180:183], v[240:243], v[70:73]
	v_mfma_f32_16x16x32_bf16 v[66:69], v[188:191], v[240:243], v[66:69]
	v_mfma_f32_16x16x32_bf16 v[118:121], v[184:187], v[220:223], v[118:121]
	v_mfma_f32_16x16x32_bf16 v[110:113], v[204:207], v[220:223], v[110:113]
	v_mfma_f32_16x16x32_bf16 v[102:105], v[184:187], v[228:231], v[102:105]
	v_mfma_f32_16x16x32_bf16 v[94:97], v[204:207], v[228:231], v[94:97]
	v_mfma_f32_16x16x32_bf16 v[86:89], v[184:187], v[236:239], v[86:89]
	v_mfma_f32_16x16x32_bf16 v[78:81], v[204:207], v[236:239], v[78:81]
	v_mfma_f32_16x16x32_bf16 v[70:73], v[184:187], v[244:247], v[70:73]
	v_mfma_f32_16x16x32_bf16 v[66:69], v[204:207], v[244:247], v[66:69]
	s_barrier
	s_setprio 0
	s_add_i32 s55, s55, s0
	v_lshl_add_u64 v[192:193], s[44:45], 0, v[0:1]
	s_mov_b32 m0, s55
	ds_read_b128 v[216:219], v166 offset:16384
	ds_read_b128 v[220:223], v166 offset:17408
	ds_read_b128 v[224:227], v166 offset:18432
	ds_read_b128 v[228:231], v166 offset:19456
	ds_read_b128 v[232:235], v166 offset:20480
	ds_read_b128 v[236:239], v166 offset:21504
	ds_read_b128 v[240:243], v166 offset:22528
	ds_read_b128 v[244:247], v166 offset:23552
	global_load_lds_dwordx4 v[192:193], off
	s_add_i32 m0, s55, 0x2000
	s_add_u32 s58, s44, 0x80000
	v_lshl_add_u64 v[248:249], s[44:45], 0, v[130:131]
	s_addc_u32 s59, s45, 0
	s_add_i32 s55, s62, s0
	global_load_lds_dwordx4 v[248:249], off
	v_lshl_add_u64 v[250:251], s[58:59], 0, v[0:1]
	s_mov_b32 m0, s55
	v_lshl_add_u64 v[200:201], s[46:47], 0, v[132:133]
	global_load_lds_dwordx4 v[250:251], off
	v_lshl_add_u64 v[250:251], s[58:59], 0, v[130:131]
	s_add_i32 m0, s55, 0x2000
	s_nop 0
	global_load_lds_dwordx4 v[250:251], off
	v_lshl_add_u64 v[250:251], s[46:47], 0, v[134:135]
	s_mov_b32 m0, s1
	s_nop 0
	global_load_lds_dwordx4 v[250:251], off
	s_mov_b32 m0, s2
	s_nop 0
	global_load_lds_dwordx4 v[200:201], off
	s_waitcnt vmcnt(8)
	s_waitcnt lgkmcnt(0)
	s_setprio 1
	s_barrier
; #define PG8_STAGE(bufoff, gbase, voff) do { _Pragma("unroll") for (int _i = 0; _i < 2; ++_i) \
;         __builtin_amdgcn_global_load_lds((const unsigned*)((const char*)(gbase) + (voff)[_i]), (PG8_LAS unsigned*)(lds + (bufoff) + ldsw + _i * 8192), 16, 0, 0); } while (0)
; #define PG8_LDA(dst, b, h) do { _Pragma("unroll") for (int m = 0; m < 4; ++m) _Pragma("unroll") for (int k = 0; k < 2; ++k) dst[m][k] = *(const PG8_LAS bf16x8*)(lds + PG8_SA(b, h) + aoff + m * 2048 + k * 1024); } while (0)
; #define PG8_LDB(dst, b, h) do { _Pragma("unroll") for (int n = 0; n < 2; ++n) _Pragma("unroll") for (int k = 0; k < 2; ++k) dst[n][k] = *(const PG8_LAS bf16x8*)(lds + PG8_SB(b, h) + boff + n * 2048 + k * 1024); } while (0)
; #define PG8_MMA(ai, bj, At, Bt) do { __builtin_amdgcn_s_setprio(1); _Pragma("unroll") for (int m = 0; m < 4; ++m) _Pragma("unroll") for (int n = 0; n < 2; ++n) _Pragma("unroll") for (int k = 0; k < 2; ++k) \
;         acc[ai][bj][m][n] = __builtin_amdgcn_mfma_f32_16x16x32_bf16(Bt[n][k], At[m][k], acc[ai][bj][m][n], 0, 0, 0); __builtin_amdgcn_s_setprio(0); } while (0)
; #define PG8_WAIT_V(n) asm volatile("s_waitcnt vmcnt(" #n ")" ::: "memory")
; #define PG8_WAIT_L(n) asm volatile("s_waitcnt lgkmcnt(" #n ")" ::: "memory")
; #define PG8_BAR __builtin_amdgcn_s_barrier()
; #define PG8_SCHED __builtin_amdgcn_sched_barrier(0)
; template <class Epi, class Sched, bool ALIGN_EPI = false, bool SP2 = false>
; __device__ __forceinline__ void gemm_phase(PG8_LAS unsigned char* lds, const Gemm g, const Sched& S, const Epi& E) {
;     ...
;             PG8_WAIT_V(8); PG8_WAIT_L(0); PG8_BAR; PG8_MMA(1, 0, At, B0); PG8_MMA(1, 1, At, B1); PG8_BAR; PG8_SCHED;
;             PG8_LDB(B0, 1, 0); PG8_LDB(B1, 1, 1); PG8_SCHED; PG8_LDA(At, 1, 0); PG8_STAGE(PG8_SA(0, 1), a2 + hstep, voffA);
;             PG8_WAIT_V(8); PG8_WAIT_L(0); PG8_BAR; PG8_MMA(0, 0, At, B0); PG8_MMA(0, 1, At, B1); PG8_BAR; PG8_SCHED;
	v_mfma_f32_16x16x32_bf16 v[62:65], v[142:145], v[216:219], v[62:65]
	v_mfma_f32_16x16x32_bf16 v[58:61], v[172:175], v[216:219], v[58:61]
	v_mfma_f32_16x16x32_bf16 v[50:53], v[142:145], v[224:227], v[50:53]
	v_mfma_f32_16x16x32_bf16 v[42:45], v[172:175], v[224:227], v[42:45]
	v_mfma_f32_16x16x32_bf16 v[34:37], v[142:145], v[232:235], v[34:37]
	v_mfma_f32_16x16x32_bf16 v[26:29], v[172:175], v[232:235], v[26:29]
	v_mfma_f32_16x16x32_bf16 v[18:21], v[142:145], v[240:243], v[18:21]
	v_mfma_f32_16x16x32_bf16 v[10:13], v[172:175], v[240:243], v[10:13]
	v_mfma_f32_16x16x32_bf16 v[62:65], v[168:171], v[220:223], v[62:65]
	v_mfma_f32_16x16x32_bf16 v[58:61], v[176:179], v[220:223], v[58:61]
	v_mfma_f32_16x16x32_bf16 v[50:53], v[168:171], v[228:231], v[50:53]
	v_mfma_f32_16x16x32_bf16 v[42:45], v[176:179], v[228:231], v[42:45]
	v_mfma_f32_16x16x32_bf16 v[34:37], v[168:171], v[236:239], v[34:37]
	v_mfma_f32_16x16x32_bf16 v[26:29], v[176:179], v[236:239], v[26:29]
	v_mfma_f32_16x16x32_bf16 v[18:21], v[168:171], v[244:247], v[18:21]
	v_mfma_f32_16x16x32_bf16 v[10:13], v[176:179], v[244:247], v[10:13]
	v_mfma_f32_16x16x32_bf16 v[54:57], v[180:183], v[216:219], v[54:57]
	v_mfma_f32_16x16x32_bf16 v[46:49], v[188:191], v[216:219], v[46:49]
	v_mfma_f32_16x16x32_bf16 v[38:41], v[180:183], v[224:227], v[38:41]
	v_mfma_f32_16x16x32_bf16 v[30:33], v[188:191], v[224:227], v[30:33]
	v_mfma_f32_16x16x32_bf16 v[22:25], v[180:183], v[232:235], v[22:25]
	v_mfma_f32_16x16x32_bf16 v[14:17], v[188:191], v[232:235], v[14:17]
	v_mfma_f32_16x16x32_bf16 v[6:9], v[180:183], v[240:243], v[6:9]
	v_mfma_f32_16x16x32_bf16 v[2:5], v[188:191], v[240:243], v[2:5]
	v_mfma_f32_16x16x32_bf16 v[54:57], v[184:187], v[220:223], v[54:57]
	v_mfma_f32_16x16x32_bf16 v[46:49], v[204:207], v[220:223], v[46:49]
	v_mfma_f32_16x16x32_bf16 v[38:41], v[184:187], v[228:231], v[38:41]
	v_mfma_f32_16x16x32_bf16 v[30:33], v[204:207], v[228:231], v[30:33]
	v_mfma_f32_16x16x32_bf16 v[22:25], v[184:187], v[236:239], v[22:25]
	v_mfma_f32_16x16x32_bf16 v[14:17], v[204:207], v[236:239], v[14:17]
	v_mfma_f32_16x16x32_bf16 v[6:9], v[184:187], v[244:247], v[6:9]
	v_mfma_f32_16x16x32_bf16 v[2:5], v[204:207], v[244:247], v[2:5]
	s_barrier
	s_setprio 0
	s_add_i32 s55, 0, 0x18000
	v_add_u32_e32 v167, s55, v147
	s_add_i32 s58, 0, 0x1c000
	ds_read_b128 v[142:145], v167
	ds_read_b128 v[168:171], v167 offset:1024
	ds_read_b128 v[172:175], v167 offset:2048
	ds_read_b128 v[176:179], v167 offset:3072
	v_add_u32_e32 v167, s58, v147
	ds_read_b128 v[180:183], v167
	ds_read_b128 v[184:187], v167 offset:1024
	ds_read_b128 v[188:191], v167 offset:2048
	ds_read_b128 v[204:207], v167 offset:3072
	s_add_u32 s46, s46, 0x80000
	s_addc_u32 s47, s47, 0
	s_mov_b32 m0, s3
	v_lshl_add_u64 v[202:203], s[46:47], 0, v[134:135]
	ds_read_b128 v[216:219], v166 offset:32768
	ds_read_b128 v[220:223], v166 offset:33792
	ds_read_b128 v[224:227], v166 offset:34816
	ds_read_b128 v[228:231], v166 offset:35840
	ds_read_b128 v[232:235], v166 offset:36864
	ds_read_b128 v[236:239], v166 offset:37888
	ds_read_b128 v[240:243], v166 offset:38912
	ds_read_b128 v[244:247], v166 offset:39936
	global_load_lds_dwordx4 v[202:203], off
	v_lshl_add_u64 v[202:203], s[46:47], 0, v[132:133]
	s_mov_b32 m0, s10
	s_nop 0
	global_load_lds_dwordx4 v[202:203], off
	s_waitcnt vmcnt(8)
	s_waitcnt lgkmcnt(0)
	s_setprio 1
	s_barrier
	v_mfma_f32_16x16x32_bf16 v[126:129], v[142:145], v[216:219], v[126:129]
	v_mfma_f32_16x16x32_bf16 v[122:125], v[172:175], v[216:219], v[122:125]
	v_mfma_f32_16x16x32_bf16 v[114:117], v[142:145], v[224:227], v[114:117]
	v_mfma_f32_16x16x32_bf16 v[106:109], v[172:175], v[224:227], v[106:109]
	v_mfma_f32_16x16x32_bf16 v[98:101], v[142:145], v[232:235], v[98:101]
	v_mfma_f32_16x16x32_bf16 v[90:93], v[172:175], v[232:235], v[90:93]
	v_mfma_f32_16x16x32_bf16 v[82:85], v[142:145], v[240:243], v[82:85]
	v_mfma_f32_16x16x32_bf16 v[74:77], v[172:175], v[240:243], v[74:77]
	v_mfma_f32_16x16x32_bf16 v[126:129], v[168:171], v[220:223], v[126:129]
	v_mfma_f32_16x16x32_bf16 v[122:125], v[176:179], v[220:223], v[122:125]
	v_mfma_f32_16x16x32_bf16 v[114:117], v[168:171], v[228:231], v[114:117]
	v_mfma_f32_16x16x32_bf16 v[106:109], v[176:179], v[228:231], v[106:109]
	v_mfma_f32_16x16x32_bf16 v[98:101], v[168:171], v[236:239], v[98:101]
	v_mfma_f32_16x16x32_bf16 v[90:93], v[176:179], v[236:239], v[90:93]
	v_mfma_f32_16x16x32_bf16 v[82:85], v[168:171], v[244:247], v[82:85]
	v_mfma_f32_16x16x32_bf16 v[74:77], v[176:179], v[244:247], v[74:77]
	v_mfma_f32_16x16x32_bf16 v[118:121], v[180:183], v[216:219], v[118:121]
	v_mfma_f32_16x16x32_bf16 v[110:113], v[188:191], v[216:219], v[110:113]
	v_mfma_f32_16x16x32_bf16 v[102:105], v[180:183], v[224:227], v[102:105]
	v_mfma_f32_16x16x32_bf16 v[94:97], v[188:191], v[224:227], v[94:97]
	v_mfma_f32_16x16x32_bf16 v[86:89], v[180:183], v[232:235], v[86:89]
	v_mfma_f32_16x16x32_bf16 v[78:81], v[188:191], v[232:235], v[78:81]
	v_mfma_f32_16x16x32_bf16 v[70:73], v[180:183], v[240:243], v[70:73]
	v_mfma_f32_16x16x32_bf16 v[66:69], v[188:191], v[240:243], v[66:69]
	v_mfma_f32_16x16x32_bf16 v[118:121], v[184:187], v[220:223], v[118:121]
	v_mfma_f32_16x16x32_bf16 v[110:113], v[204:207], v[220:223], v[110:113]
	v_mfma_f32_16x16x32_bf16 v[102:105], v[184:187], v[228:231], v[102:105]
	v_mfma_f32_16x16x32_bf16 v[94:97], v[204:207], v[228:231], v[94:97]
	v_mfma_f32_16x16x32_bf16 v[86:89], v[184:187], v[236:239], v[86:89]
	v_mfma_f32_16x16x32_bf16 v[78:81], v[204:207], v[236:239], v[78:81]
	v_mfma_f32_16x16x32_bf16 v[70:73], v[184:187], v[244:247], v[70:73]
	v_mfma_f32_16x16x32_bf16 v[66:69], v[204:207], v[244:247], v[66:69]
	s_barrier
; #define PG8_STAGE(bufoff, gbase, voff) do { _Pragma("unroll") for (int _i = 0; _i < 2; ++_i) \
;         __builtin_amdgcn_global_load_lds((const unsigned*)((const char*)(gbase) + (voff)[_i]), (PG8_LAS unsigned*)(lds + (bufoff) + ldsw + _i * 8192), 16, 0, 0); } while (0)
; #define PG8_LDA(dst, b, h) do { _Pragma("unroll") for (int m = 0; m < 4; ++m) _Pragma("unroll") for (int k = 0; k < 2; ++k) dst[m][k] = *(const PG8_LAS bf16x8*)(lds + PG8_SA(b, h) + aoff + m * 2048 + k * 1024); } while (0)
; #define PG8_MMA(ai, bj, At, Bt) do { __builtin_amdgcn_s_setprio(1); _Pragma("unroll") for (int m = 0; m < 4; ++m) _Pragma("unroll") for (int n = 0; n < 2; ++n) _Pragma("unroll") for (int k = 0; k < 2; ++k) \
;         acc[ai][bj][m][n] = __builtin_amdgcn_mfma_f32_16x16x32_bf16(Bt[n][k], At[m][k], acc[ai][bj][m][n], 0, 0, 0); __builtin_amdgcn_s_setprio(0); } while (0)
; #define PG8_WAIT_V(n) asm volatile("s_waitcnt vmcnt(" #n ")" ::: "memory")
; #define PG8_WAIT_L(n) asm volatile("s_waitcnt lgkmcnt(" #n ")" ::: "memory")
; #define PG8_BAR __builtin_amdgcn_s_barrier()
; #define PG8_SCHED __builtin_amdgcn_sched_barrier(0)
; template <class Epi, class Sched, bool ALIGN_EPI = false, bool SP2 = false>
; __device__ __forceinline__ void gemm_phase(PG8_LAS unsigned char* lds, const Gemm g, const Sched& S, const Epi& E) {
;     ...
;         for (int t = 0; t < nt; t += 2) {
;             const bool last = (t == nt - 2);
;             const char* a1 = cA + (size_t)(t + 1) * kstep;
;             const char* a2 = last ? nA : cA + (size_t)(t + 2) * kstep; const char* b2 = last ? nB : cB + (size_t)(t + 2) * kstep;
;     ...
;             PG8_LDA(At, 1, 1); PG8_STAGE(PG8_SB(1, 0), b3, voffB); PG8_STAGE(PG8_SB(1, 1), b3 + hstep, voffB); PG8_STAGE(PG8_SA(1, 0), a3, voffA);
;             PG8_WAIT_V(8); PG8_WAIT_L(0); PG8_BAR; PG8_MMA(1, 0, At, B0); PG8_MMA(1, 1, At, B1); PG8_BAR; PG8_SCHED;
	s_setprio 0
	s_add_i32 s46, s55, s0
	v_lshl_add_u64 v[192:193], v[192:193], 0, s[56:57]
	s_mov_b32 m0, s46
	ds_read_b128 v[216:219], v166 offset:49152
	ds_read_b128 v[220:223], v166 offset:50176
	ds_read_b128 v[224:227], v166 offset:51200
	ds_read_b128 v[228:231], v166 offset:52224
	ds_read_b128 v[232:235], v166 offset:53248
	ds_read_b128 v[236:239], v166 offset:54272
	ds_read_b128 v[240:243], v166 offset:55296
	ds_read_b128 v[244:247], v166 offset:56320
	global_load_lds_dwordx4 v[192:193], off
	s_add_i32 m0, s46, 0x2000
	s_add_u32 s44, s44, 0x80080
	v_lshl_add_u64 v[192:193], v[248:249], 0, s[56:57]
	s_addc_u32 s45, s45, 0
	s_add_i32 s46, s58, s0
	global_load_lds_dwordx4 v[192:193], off
	v_lshl_add_u64 v[192:193], s[44:45], 0, v[0:1]
	s_mov_b32 m0, s46
	s_nop 0
	global_load_lds_dwordx4 v[192:193], off
	v_lshl_add_u64 v[192:193], s[44:45], 0, v[130:131]
	s_add_i32 m0, s46, 0x2000
	s_nop 0
	global_load_lds_dwordx4 v[192:193], off
	v_lshl_add_u64 v[192:193], v[250:251], 0, s[56:57]
	s_mov_b32 m0, s11
	s_nop 0
	global_load_lds_dwordx4 v[192:193], off
	v_lshl_add_u64 v[192:193], v[200:201], 0, s[56:57]
	s_mov_b32 m0, s26
	s_nop 0
	global_load_lds_dwordx4 v[192:193], off
	s_waitcnt vmcnt(8)
	s_waitcnt lgkmcnt(0)
	s_setprio 1
	s_barrier
	v_mfma_f32_16x16x32_bf16 v[62:65], v[142:145], v[216:219], v[62:65]
	v_mfma_f32_16x16x32_bf16 v[58:61], v[172:175], v[216:219], v[58:61]
	v_mfma_f32_16x16x32_bf16 v[50:53], v[142:145], v[224:227], v[50:53]
	v_mfma_f32_16x16x32_bf16 v[42:45], v[172:175], v[224:227], v[42:45]
	v_mfma_f32_16x16x32_bf16 v[34:37], v[142:145], v[232:235], v[34:37]
	v_mfma_f32_16x16x32_bf16 v[26:29], v[172:175], v[232:235], v[26:29]
	v_mfma_f32_16x16x32_bf16 v[18:21], v[142:145], v[240:243], v[18:21]
	v_mfma_f32_16x16x32_bf16 v[10:13], v[172:175], v[240:243], v[10:13]
	v_mfma_f32_16x16x32_bf16 v[62:65], v[168:171], v[220:223], v[62:65]
	v_mfma_f32_16x16x32_bf16 v[58:61], v[176:179], v[220:223], v[58:61]
	v_mfma_f32_16x16x32_bf16 v[50:53], v[168:171], v[228:231], v[50:53]
	v_mfma_f32_16x16x32_bf16 v[42:45], v[176:179], v[228:231], v[42:45]
	v_mfma_f32_16x16x32_bf16 v[34:37], v[168:171], v[236:239], v[34:37]
	v_mfma_f32_16x16x32_bf16 v[26:29], v[176:179], v[236:239], v[26:29]
	v_mfma_f32_16x16x32_bf16 v[18:21], v[168:171], v[244:247], v[18:21]
	v_mfma_f32_16x16x32_bf16 v[10:13], v[176:179], v[244:247], v[10:13]
	v_mfma_f32_16x16x32_bf16 v[54:57], v[180:183], v[216:219], v[54:57]
	v_mfma_f32_16x16x32_bf16 v[46:49], v[188:191], v[216:219], v[46:49]
	v_mfma_f32_16x16x32_bf16 v[38:41], v[180:183], v[224:227], v[38:41]
	v_mfma_f32_16x16x32_bf16 v[30:33], v[188:191], v[224:227], v[30:33]
	v_mfma_f32_16x16x32_bf16 v[22:25], v[180:183], v[232:235], v[22:25]
	v_mfma_f32_16x16x32_bf16 v[14:17], v[188:191], v[232:235], v[14:17]
	v_mfma_f32_16x16x32_bf16 v[6:9], v[180:183], v[240:243], v[6:9]
	v_mfma_f32_16x16x32_bf16 v[2:5], v[188:191], v[240:243], v[2:5]
	v_mfma_f32_16x16x32_bf16 v[54:57], v[184:187], v[220:223], v[54:57]
	v_mfma_f32_16x16x32_bf16 v[46:49], v[204:207], v[220:223], v[46:49]
	v_mfma_f32_16x16x32_bf16 v[38:41], v[184:187], v[228:231], v[38:41]
	v_mfma_f32_16x16x32_bf16 v[30:33], v[204:207], v[228:231], v[30:33]
	v_mfma_f32_16x16x32_bf16 v[22:25], v[184:187], v[236:239], v[22:25]
	v_mfma_f32_16x16x32_bf16 v[14:17], v[204:207], v[236:239], v[14:17]
	v_mfma_f32_16x16x32_bf16 v[6:9], v[184:187], v[244:247], v[6:9]
	v_mfma_f32_16x16x32_bf16 v[2:5], v[204:207], v[244:247], v[2:5]
	s_barrier
	s_setprio 0
	s_add_i32 s54, s54, 2
	s_add_u32 s24, s24, 0x100
	s_addc_u32 s25, s25, 0
	s_add_u32 s50, s50, 0x100
	s_addc_u32 s51, s51, 0
	s_cmp_gt_u32 s54, 29
	s_cbranch_scc0 .LBB0_146
	s_and_b64 vcc, exec, s[16:17]
	s_cbranch_vccz .LBB0_149
	s_barrier

; #define PG8_STAGE(bufoff, gbase, voff) do { _Pragma("unroll") for (int _i = 0; _i < 2; ++_i) \
;         __builtin_amdgcn_global_load_lds((const unsigned*)((const char*)(gbase) + (voff)[_i]), (PG8_LAS unsigned*)(lds + (bufoff) + ldsw + _i * 8192), 16, 0, 0); } while (0)
; #define PG8_LDA(dst, b, h) do { _Pragma("unroll") for (int m = 0; m < 4; ++m) _Pragma("unroll") for (int k = 0; k < 2; ++k) dst[m][k] = *(const PG8_LAS bf16x8*)(lds + PG8_SA(b, h) + aoff + m * 2048 + k * 1024); } while (0)
; #define PG8_LDB(dst, b, h) do { _Pragma("unroll") for (int n = 0; n < 2; ++n) _Pragma("unroll") for (int k = 0; k < 2; ++k) dst[n][k] = *(const PG8_LAS bf16x8*)(lds + PG8_SB(b, h) + boff + n * 2048 + k * 1024); } while (0)
; #define PG8_MMA(ai, bj, At, Bt) do { __builtin_amdgcn_s_setprio(1); _Pragma("unroll") for (int m = 0; m < 4; ++m) _Pragma("unroll") for (int n = 0; n < 2; ++n) _Pragma("unroll") for (int k = 0; k < 2; ++k) \
;         acc[ai][bj][m][n] = __builtin_amdgcn_mfma_f32_16x16x32_bf16(Bt[n][k], At[m][k], acc[ai][bj][m][n], 0, 0, 0); __builtin_amdgcn_s_setprio(0); } while (0)
; #define PG8_WAIT_V(n) asm volatile("s_waitcnt vmcnt(" #n ")" ::: "memory")
; #define PG8_WAIT_L(n) asm volatile("s_waitcnt lgkmcnt(" #n ")" ::: "memory")
; template <class Epi, class Sched, bool ALIGN_EPI = false, bool SP2 = false>
; __device__ __forceinline__ void gemm_phase(PG8_LAS unsigned char* lds, const Gemm g, const Sched& S, const Epi& E) {
;     ...
;             const bool last = (t == nt - 2);
;             const char* a1 = cA + (size_t)(t + 1) * kstep;
;             const char* a2 = last ? nA : cA + (size_t)(t + 2) * kstep; const char* b2 = last ? nB : cB + (size_t)(t + 2) * kstep;
;             const char* a3 = a2 + kstep; const char* b3 = b2 + kstep;
;             if (last && has_next) S.a_ready(nxt);
;             if constexpr (SP2) {
;             PG8_LDB(B0, 0, 0); PG8_LDB(B1, 0, 1); PG8_SCHED; PG8_LDA(At, 0, 0); PG8_STAGE(PG8_SA(1, 1), a1 + hstep, voffA);
;             PG8_WAIT_V(8); PG8_WAIT_L(0); PG8_BAR; PG8_MMA(0, 0, At, B0); PG8_MMA(0, 1, At, B1); PG8_BAR; PG8_SCHED;
;             PG8_LDA(At, 0, 1); PG8_STAGE(PG8_SB(0, 0), b2, voffB); PG8_STAGE(PG8_SB(0, 1), b2 + hstep, voffB); PG8_STAGE(PG8_SA(0, 0), a2, voffA);
;             PG8_WAIT_V(8); PG8_WAIT_L(0); PG8_BAR; PG8_MMA(1, 0, At, B0); PG8_MMA(1, 1, At, B1); PG8_BAR; PG8_SCHED;
.LBB0_489:
	s_add_u32 s50, s24, 0xfff80080
	s_addc_u32 s51, s25, -1
	s_add_i32 s66, 0, 0x10000
	s_cmp_eq_u32 s63, 28
	s_cselect_b32 s59, s15, s51
	s_cselect_b32 s58, s23, s50
	s_cselect_b32 s51, s21, s62
	s_cselect_b32 s50, s26, s27
	s_add_i32 s68, 0, 0x14000
	v_add_u32_e32 v152, s66, v163
	v_add_u32_e32 v160, s68, v163
	ds_read_b128 v[130:133], v152
	ds_read_b128 v[134:137], v152 offset:1024
	ds_read_b128 v[138:141], v152 offset:2048
	ds_read_b128 v[152:155], v152 offset:3072
	ds_read_b128 v[156:159], v160
	ds_read_b128 v[166:169], v160 offset:1024
	ds_read_b128 v[170:173], v160 offset:2048
	ds_read_b128 v[174:177], v160 offset:3072
	v_lshl_add_u64 v[160:161], s[24:25], 0, v[148:149]
	s_add_i32 m0, s3, 0xc000
	ds_read_b128 v[178:181], v165
	ds_read_b128 v[182:185], v165 offset:1024
	ds_read_b128 v[186:189], v165 offset:2048
	ds_read_b128 v[190:193], v165 offset:3072
	ds_read_b128 v[204:207], v165 offset:4096
	ds_read_b128 v[218:221], v165 offset:5120
	ds_read_b128 v[222:225], v165 offset:6144
	ds_read_b128 v[226:229], v165 offset:7168
	global_load_lds_dwordx4 v[160:161], off
	v_lshl_add_u64 v[160:161], s[24:25], 0, v[150:151]
	s_add_i32 m0, s3, 0xe000
	s_nop 0
	global_load_lds_dwordx4 v[160:161], off
	s_waitcnt vmcnt(8)
	s_waitcnt lgkmcnt(0)
	s_setprio 1
	s_barrier
	v_mfma_f32_16x16x32_bf16 v[126:129], v[130:133], v[178:181], v[126:129]
	v_mfma_f32_16x16x32_bf16 v[122:125], v[138:141], v[178:181], v[122:125]
	v_mfma_f32_16x16x32_bf16 v[110:113], v[130:133], v[186:189], v[110:113]
	v_mfma_f32_16x16x32_bf16 v[106:109], v[138:141], v[186:189], v[106:109]
	v_mfma_f32_16x16x32_bf16 v[94:97], v[130:133], v[204:207], v[94:97]
	v_mfma_f32_16x16x32_bf16 v[90:93], v[138:141], v[204:207], v[90:93]
	v_mfma_f32_16x16x32_bf16 v[78:81], v[130:133], v[222:225], v[78:81]
	v_mfma_f32_16x16x32_bf16 v[74:77], v[138:141], v[222:225], v[74:77]
	v_mfma_f32_16x16x32_bf16 v[126:129], v[134:137], v[182:185], v[126:129]
	v_mfma_f32_16x16x32_bf16 v[122:125], v[152:155], v[182:185], v[122:125]
	v_mfma_f32_16x16x32_bf16 v[110:113], v[134:137], v[190:193], v[110:113]
	v_mfma_f32_16x16x32_bf16 v[106:109], v[152:155], v[190:193], v[106:109]
	v_mfma_f32_16x16x32_bf16 v[94:97], v[134:137], v[218:221], v[94:97]
	v_mfma_f32_16x16x32_bf16 v[90:93], v[152:155], v[218:221], v[90:93]
	v_mfma_f32_16x16x32_bf16 v[78:81], v[134:137], v[226:229], v[78:81]
	v_mfma_f32_16x16x32_bf16 v[74:77], v[152:155], v[226:229], v[74:77]
	v_mfma_f32_16x16x32_bf16 v[118:121], v[156:159], v[178:181], v[118:121]
	v_mfma_f32_16x16x32_bf16 v[114:117], v[170:173], v[178:181], v[114:117]
	v_mfma_f32_16x16x32_bf16 v[102:105], v[156:159], v[186:189], v[102:105]
	v_mfma_f32_16x16x32_bf16 v[98:101], v[170:173], v[186:189], v[98:101]
	v_mfma_f32_16x16x32_bf16 v[86:89], v[156:159], v[204:207], v[86:89]
	v_mfma_f32_16x16x32_bf16 v[82:85], v[170:173], v[204:207], v[82:85]
	v_mfma_f32_16x16x32_bf16 v[70:73], v[156:159], v[222:225], v[70:73]
	v_mfma_f32_16x16x32_bf16 v[66:69], v[170:173], v[222:225], v[66:69]
	v_mfma_f32_16x16x32_bf16 v[118:121], v[166:169], v[182:185], v[118:121]
	v_mfma_f32_16x16x32_bf16 v[114:117], v[174:177], v[182:185], v[114:117]
	v_mfma_f32_16x16x32_bf16 v[102:105], v[166:169], v[190:193], v[102:105]
	v_mfma_f32_16x16x32_bf16 v[98:101], v[174:177], v[190:193], v[98:101]
	v_mfma_f32_16x16x32_bf16 v[86:89], v[166:169], v[218:221], v[86:89]
	v_mfma_f32_16x16x32_bf16 v[82:85], v[174:177], v[218:221], v[82:85]
	v_mfma_f32_16x16x32_bf16 v[70:73], v[166:169], v[226:229], v[70:73]
	v_mfma_f32_16x16x32_bf16 v[66:69], v[174:177], v[226:229], v[66:69]
	s_barrier
	s_setprio 0
	s_add_i32 s66, s66, s2
	v_lshl_add_u64 v[160:161], s[50:51], 0, v[0:1]
	s_mov_b32 m0, s66
	ds_read_b128 v[178:181], v165 offset:16384
	ds_read_b128 v[182:185], v165 offset:17408
	ds_read_b128 v[186:189], v165 offset:18432
	ds_read_b128 v[190:193], v165 offset:19456
	ds_read_b128 v[204:207], v165 offset:20480
	ds_read_b128 v[218:221], v165 offset:21504
	ds_read_b128 v[222:225], v165 offset:22528
	ds_read_b128 v[226:229], v165 offset:23552
	global_load_lds_dwordx4 v[160:161], off
	s_add_i32 m0, s66, 0x2000
	s_add_u32 s66, s50, 0x80000
	v_lshl_add_u64 v[200:201], s[50:51], 0, v[146:147]
	s_addc_u32 s67, s51, 0
	s_add_i32 s68, s68, s2
	global_load_lds_dwordx4 v[200:201], off
	v_lshl_add_u64 v[202:203], s[66:67], 0, v[0:1]
	s_mov_b32 m0, s68
	v_lshl_add_u64 v[230:231], s[58:59], 0, v[144:145]
	global_load_lds_dwordx4 v[202:203], off
	v_lshl_add_u64 v[202:203], s[66:67], 0, v[146:147]
	s_add_i32 m0, s68, 0x2000
	s_nop 0
	global_load_lds_dwordx4 v[202:203], off
	v_lshl_add_u64 v[202:203], s[58:59], 0, v[142:143]
	s_mov_b32 m0, s3
	s_nop 0
	global_load_lds_dwordx4 v[202:203], off
	s_mov_b32 m0, s10
	s_nop 0
	global_load_lds_dwordx4 v[230:231], off
	s_waitcnt vmcnt(8)
	s_waitcnt lgkmcnt(0)
	s_setprio 1
	s_barrier
; #define PG8_STAGE(bufoff, gbase, voff) do { _Pragma("unroll") for (int _i = 0; _i < 2; ++_i) \
;         __builtin_amdgcn_global_load_lds((const unsigned*)((const char*)(gbase) + (voff)[_i]), (PG8_LAS unsigned*)(lds + (bufoff) + ldsw + _i * 8192), 16, 0, 0); } while (0)
; #define PG8_LDA(dst, b, h) do { _Pragma("unroll") for (int m = 0; m < 4; ++m) _Pragma("unroll") for (int k = 0; k < 2; ++k) dst[m][k] = *(const PG8_LAS bf16x8*)(lds + PG8_SA(b, h) + aoff + m * 2048 + k * 1024); } while (0)
; #define PG8_LDB(dst, b, h) do { _Pragma("unroll") for (int n = 0; n < 2; ++n) _Pragma("unroll") for (int k = 0; k < 2; ++k) dst[n][k] = *(const PG8_LAS bf16x8*)(lds + PG8_SB(b, h) + boff + n * 2048 + k * 1024); } while (0)
; #define PG8_MMA(ai, bj, At, Bt) do { __builtin_amdgcn_s_setprio(1); _Pragma("unroll") for (int m = 0; m < 4; ++m) _Pragma("unroll") for (int n = 0; n < 2; ++n) _Pragma("unroll") for (int k = 0; k < 2; ++k) \
;         acc[ai][bj][m][n] = __builtin_amdgcn_mfma_f32_16x16x32_bf16(Bt[n][k], At[m][k], acc[ai][bj][m][n], 0, 0, 0); __builtin_amdgcn_s_setprio(0); } while (0)
; #define PG8_WAIT_V(n) asm volatile("s_waitcnt vmcnt(" #n ")" ::: "memory")
; #define PG8_WAIT_L(n) asm volatile("s_waitcnt lgkmcnt(" #n ")" ::: "memory")
; #define PG8_BAR __builtin_amdgcn_s_barrier()
; #define PG8_SCHED __builtin_amdgcn_sched_barrier(0)
; template <class Epi, class Sched, bool ALIGN_EPI = false, bool SP2 = false>
; __device__ __forceinline__ void gemm_phase(PG8_LAS unsigned char* lds, const Gemm g, const Sched& S, const Epi& E) {
;     ...
;             PG8_WAIT_V(8); PG8_WAIT_L(0); PG8_BAR; PG8_MMA(1, 0, At, B0); PG8_MMA(1, 1, At, B1); PG8_BAR; PG8_SCHED;
;             PG8_LDB(B0, 1, 0); PG8_LDB(B1, 1, 1); PG8_SCHED; PG8_LDA(At, 1, 0); PG8_STAGE(PG8_SA(0, 1), a2 + hstep, voffA);
;             PG8_WAIT_V(8); PG8_WAIT_L(0); PG8_BAR; PG8_MMA(0, 0, At, B0); PG8_MMA(0, 1, At, B1); PG8_BAR; PG8_SCHED;
	v_mfma_f32_16x16x32_bf16 v[62:65], v[130:133], v[178:181], v[62:65]
	v_mfma_f32_16x16x32_bf16 v[58:61], v[138:141], v[178:181], v[58:61]
	v_mfma_f32_16x16x32_bf16 v[46:49], v[130:133], v[186:189], v[46:49]
	v_mfma_f32_16x16x32_bf16 v[42:45], v[138:141], v[186:189], v[42:45]
	v_mfma_f32_16x16x32_bf16 v[30:33], v[130:133], v[204:207], v[30:33]
	v_mfma_f32_16x16x32_bf16 v[26:29], v[138:141], v[204:207], v[26:29]
	v_mfma_f32_16x16x32_bf16 v[14:17], v[130:133], v[222:225], v[14:17]
	v_mfma_f32_16x16x32_bf16 v[10:13], v[138:141], v[222:225], v[10:13]
	v_mfma_f32_16x16x32_bf16 v[62:65], v[134:137], v[182:185], v[62:65]
	v_mfma_f32_16x16x32_bf16 v[58:61], v[152:155], v[182:185], v[58:61]
	v_mfma_f32_16x16x32_bf16 v[46:49], v[134:137], v[190:193], v[46:49]
	v_mfma_f32_16x16x32_bf16 v[42:45], v[152:155], v[190:193], v[42:45]
	v_mfma_f32_16x16x32_bf16 v[30:33], v[134:137], v[218:221], v[30:33]
	v_mfma_f32_16x16x32_bf16 v[26:29], v[152:155], v[218:221], v[26:29]
	v_mfma_f32_16x16x32_bf16 v[14:17], v[134:137], v[226:229], v[14:17]
	v_mfma_f32_16x16x32_bf16 v[10:13], v[152:155], v[226:229], v[10:13]
	v_mfma_f32_16x16x32_bf16 v[54:57], v[156:159], v[178:181], v[54:57]
	v_mfma_f32_16x16x32_bf16 v[50:53], v[170:173], v[178:181], v[50:53]
	v_mfma_f32_16x16x32_bf16 v[38:41], v[156:159], v[186:189], v[38:41]
	v_mfma_f32_16x16x32_bf16 v[34:37], v[170:173], v[186:189], v[34:37]
	v_mfma_f32_16x16x32_bf16 v[22:25], v[156:159], v[204:207], v[22:25]
	v_mfma_f32_16x16x32_bf16 v[18:21], v[170:173], v[204:207], v[18:21]
	v_mfma_f32_16x16x32_bf16 v[6:9], v[156:159], v[222:225], v[6:9]
	v_mfma_f32_16x16x32_bf16 v[2:5], v[170:173], v[222:225], v[2:5]
	v_mfma_f32_16x16x32_bf16 v[54:57], v[166:169], v[182:185], v[54:57]
	v_mfma_f32_16x16x32_bf16 v[50:53], v[174:177], v[182:185], v[50:53]
	v_mfma_f32_16x16x32_bf16 v[38:41], v[166:169], v[190:193], v[38:41]
	v_mfma_f32_16x16x32_bf16 v[34:37], v[174:177], v[190:193], v[34:37]
	v_mfma_f32_16x16x32_bf16 v[22:25], v[166:169], v[218:221], v[22:25]
	v_mfma_f32_16x16x32_bf16 v[18:21], v[174:177], v[218:221], v[18:21]
	v_mfma_f32_16x16x32_bf16 v[6:9], v[166:169], v[226:229], v[6:9]
	v_mfma_f32_16x16x32_bf16 v[2:5], v[174:177], v[226:229], v[2:5]
	s_barrier
	s_setprio 0
	s_add_i32 s66, 0, 0x18000
	s_add_i32 s67, 0, 0x1c000
	v_add_u32_e32 v152, s66, v163
	v_add_u32_e32 v174, s67, v163
	ds_read_b128 v[130:133], v152
	ds_read_b128 v[134:137], v152 offset:1024
	ds_read_b128 v[138:141], v152 offset:2048
	ds_read_b128 v[152:155], v152 offset:3072
	ds_read_b128 v[156:159], v174
	ds_read_b128 v[166:169], v174 offset:1024
	ds_read_b128 v[170:173], v174 offset:2048
	ds_read_b128 v[174:177], v174 offset:3072
	s_add_u32 s58, s58, 0x80000
	s_addc_u32 s59, s59, 0
	s_mov_b32 m0, s11
	v_lshl_add_u64 v[232:233], s[58:59], 0, v[142:143]
	ds_read_b128 v[178:181], v165 offset:32768
	ds_read_b128 v[182:185], v165 offset:33792
	ds_read_b128 v[186:189], v165 offset:34816
	ds_read_b128 v[190:193], v165 offset:35840
	ds_read_b128 v[204:207], v165 offset:36864
	ds_read_b128 v[218:221], v165 offset:37888
	ds_read_b128 v[222:225], v165 offset:38912
	ds_read_b128 v[226:229], v165 offset:39936
	global_load_lds_dwordx4 v[232:233], off
	v_lshl_add_u64 v[232:233], s[58:59], 0, v[144:145]
	s_mov_b32 m0, s33
	s_nop 0
	global_load_lds_dwordx4 v[232:233], off
	s_waitcnt vmcnt(8)
	s_waitcnt lgkmcnt(0)
	s_setprio 1
	s_barrier
	v_mfma_f32_16x16x32_bf16 v[126:129], v[130:133], v[178:181], v[126:129]
	v_mfma_f32_16x16x32_bf16 v[122:125], v[138:141], v[178:181], v[122:125]
	v_mfma_f32_16x16x32_bf16 v[110:113], v[130:133], v[186:189], v[110:113]
	v_mfma_f32_16x16x32_bf16 v[106:109], v[138:141], v[186:189], v[106:109]
	v_mfma_f32_16x16x32_bf16 v[94:97], v[130:133], v[204:207], v[94:97]
	v_mfma_f32_16x16x32_bf16 v[90:93], v[138:141], v[204:207], v[90:93]
	v_mfma_f32_16x16x32_bf16 v[78:81], v[130:133], v[222:225], v[78:81]
	v_mfma_f32_16x16x32_bf16 v[74:77], v[138:141], v[222:225], v[74:77]
	v_mfma_f32_16x16x32_bf16 v[126:129], v[134:137], v[182:185], v[126:129]
	v_mfma_f32_16x16x32_bf16 v[122:125], v[152:155], v[182:185], v[122:125]
	v_mfma_f32_16x16x32_bf16 v[110:113], v[134:137], v[190:193], v[110:113]
	v_mfma_f32_16x16x32_bf16 v[106:109], v[152:155], v[190:193], v[106:109]
	v_mfma_f32_16x16x32_bf16 v[94:97], v[134:137], v[218:221], v[94:97]
	v_mfma_f32_16x16x32_bf16 v[90:93], v[152:155], v[218:221], v[90:93]
	v_mfma_f32_16x16x32_bf16 v[78:81], v[134:137], v[226:229], v[78:81]
	v_mfma_f32_16x16x32_bf16 v[74:77], v[152:155], v[226:229], v[74:77]
	v_mfma_f32_16x16x32_bf16 v[118:121], v[156:159], v[178:181], v[118:121]
	v_mfma_f32_16x16x32_bf16 v[114:117], v[170:173], v[178:181], v[114:117]
	v_mfma_f32_16x16x32_bf16 v[102:105], v[156:159], v[186:189], v[102:105]
	v_mfma_f32_16x16x32_bf16 v[98:101], v[170:173], v[186:189], v[98:101]
	v_mfma_f32_16x16x32_bf16 v[86:89], v[156:159], v[204:207], v[86:89]
	v_mfma_f32_16x16x32_bf16 v[82:85], v[170:173], v[204:207], v[82:85]
	v_mfma_f32_16x16x32_bf16 v[70:73], v[156:159], v[222:225], v[70:73]
	v_mfma_f32_16x16x32_bf16 v[66:69], v[170:173], v[222:225], v[66:69]
	v_mfma_f32_16x16x32_bf16 v[118:121], v[166:169], v[182:185], v[118:121]
	v_mfma_f32_16x16x32_bf16 v[114:117], v[174:177], v[182:185], v[114:117]
	v_mfma_f32_16x16x32_bf16 v[102:105], v[166:169], v[190:193], v[102:105]
	v_mfma_f32_16x16x32_bf16 v[98:101], v[174:177], v[190:193], v[98:101]
	v_mfma_f32_16x16x32_bf16 v[86:89], v[166:169], v[218:221], v[86:89]
	v_mfma_f32_16x16x32_bf16 v[82:85], v[174:177], v[218:221], v[82:85]
	v_mfma_f32_16x16x32_bf16 v[70:73], v[166:169], v[226:229], v[70:73]
	v_mfma_f32_16x16x32_bf16 v[66:69], v[174:177], v[226:229], v[66:69]
	s_barrier
; #define PG8_STAGE(bufoff, gbase, voff) do { _Pragma("unroll") for (int _i = 0; _i < 2; ++_i) \
;         __builtin_amdgcn_global_load_lds((const unsigned*)((const char*)(gbase) + (voff)[_i]), (PG8_LAS unsigned*)(lds + (bufoff) + ldsw + _i * 8192), 16, 0, 0); } while (0)
; #define PG8_LDA(dst, b, h) do { _Pragma("unroll") for (int m = 0; m < 4; ++m) _Pragma("unroll") for (int k = 0; k < 2; ++k) dst[m][k] = *(const PG8_LAS bf16x8*)(lds + PG8_SA(b, h) + aoff + m * 2048 + k * 1024); } while (0)
; #define PG8_MMA(ai, bj, At, Bt) do { __builtin_amdgcn_s_setprio(1); _Pragma("unroll") for (int m = 0; m < 4; ++m) _Pragma("unroll") for (int n = 0; n < 2; ++n) _Pragma("unroll") for (int k = 0; k < 2; ++k) \
;         acc[ai][bj][m][n] = __builtin_amdgcn_mfma_f32_16x16x32_bf16(Bt[n][k], At[m][k], acc[ai][bj][m][n], 0, 0, 0); __builtin_amdgcn_s_setprio(0); } while (0)
; #define PG8_WAIT_V(n) asm volatile("s_waitcnt vmcnt(" #n ")" ::: "memory")
; #define PG8_WAIT_L(n) asm volatile("s_waitcnt lgkmcnt(" #n ")" ::: "memory")
; #define PG8_BAR __builtin_amdgcn_s_barrier()
; #define PG8_SCHED __builtin_amdgcn_sched_barrier(0)
; template <class Epi, class Sched, bool ALIGN_EPI = false, bool SP2 = false>
; __device__ __forceinline__ void gemm_phase(PG8_LAS unsigned char* lds, const Gemm g, const Sched& S, const Epi& E) {
;     ...
;         for (int t = 0; t < nt; t += 2) {
;             const bool last = (t == nt - 2);
;             const char* a1 = cA + (size_t)(t + 1) * kstep;
;             const char* a2 = last ? nA : cA + (size_t)(t + 2) * kstep; const char* b2 = last ? nB : cB + (size_t)(t + 2) * kstep;
;     ...
;             PG8_LDA(At, 1, 1); PG8_STAGE(PG8_SB(1, 0), b3, voffB); PG8_STAGE(PG8_SB(1, 1), b3 + hstep, voffB); PG8_STAGE(PG8_SA(1, 0), a3, voffA);
;             PG8_WAIT_V(8); PG8_WAIT_L(0); PG8_BAR; PG8_MMA(1, 0, At, B0); PG8_MMA(1, 1, At, B1); PG8_BAR; PG8_SCHED;
	s_setprio 0
	s_add_i32 s58, s66, s2
	v_lshl_add_u64 v[160:161], v[160:161], 0, s[56:57]
	s_mov_b32 m0, s58
	ds_read_b128 v[178:181], v165 offset:49152
	ds_read_b128 v[182:185], v165 offset:50176
	ds_read_b128 v[186:189], v165 offset:51200
	ds_read_b128 v[190:193], v165 offset:52224
	ds_read_b128 v[204:207], v165 offset:53248
	ds_read_b128 v[218:221], v165 offset:54272
	ds_read_b128 v[222:225], v165 offset:55296
	ds_read_b128 v[226:229], v165 offset:56320
	global_load_lds_dwordx4 v[160:161], off
	s_add_i32 m0, s58, 0x2000
	s_add_u32 s50, s50, 0x80080
	v_lshl_add_u64 v[160:161], v[200:201], 0, s[56:57]
	s_addc_u32 s51, s51, 0
	s_add_i32 s58, s67, s2
	global_load_lds_dwordx4 v[160:161], off
	v_lshl_add_u64 v[160:161], s[50:51], 0, v[0:1]
	s_mov_b32 m0, s58
	s_nop 0
	global_load_lds_dwordx4 v[160:161], off
	v_lshl_add_u64 v[160:161], s[50:51], 0, v[146:147]
	s_add_i32 m0, s58, 0x2000
	s_nop 0
	global_load_lds_dwordx4 v[160:161], off
	v_lshl_add_u64 v[160:161], v[202:203], 0, s[56:57]
	s_mov_b32 m0, s49
	s_nop 0
	global_load_lds_dwordx4 v[160:161], off
	v_lshl_add_u64 v[160:161], v[230:231], 0, s[56:57]
	s_mov_b32 m0, s54
	s_nop 0
	global_load_lds_dwordx4 v[160:161], off
	s_waitcnt vmcnt(8)
	s_waitcnt lgkmcnt(0)
	s_setprio 1
	s_barrier
	v_mfma_f32_16x16x32_bf16 v[62:65], v[130:133], v[178:181], v[62:65]
	v_mfma_f32_16x16x32_bf16 v[58:61], v[138:141], v[178:181], v[58:61]
	v_mfma_f32_16x16x32_bf16 v[46:49], v[130:133], v[186:189], v[46:49]
	v_mfma_f32_16x16x32_bf16 v[42:45], v[138:141], v[186:189], v[42:45]
	v_mfma_f32_16x16x32_bf16 v[30:33], v[130:133], v[204:207], v[30:33]
	v_mfma_f32_16x16x32_bf16 v[26:29], v[138:141], v[204:207], v[26:29]
	v_mfma_f32_16x16x32_bf16 v[14:17], v[130:133], v[222:225], v[14:17]
	v_mfma_f32_16x16x32_bf16 v[10:13], v[138:141], v[222:225], v[10:13]
	v_mfma_f32_16x16x32_bf16 v[62:65], v[134:137], v[182:185], v[62:65]
	v_mfma_f32_16x16x32_bf16 v[58:61], v[152:155], v[182:185], v[58:61]
	v_mfma_f32_16x16x32_bf16 v[46:49], v[134:137], v[190:193], v[46:49]
	v_mfma_f32_16x16x32_bf16 v[42:45], v[152:155], v[190:193], v[42:45]
	v_mfma_f32_16x16x32_bf16 v[30:33], v[134:137], v[218:221], v[30:33]
	v_mfma_f32_16x16x32_bf16 v[26:29], v[152:155], v[218:221], v[26:29]
	v_mfma_f32_16x16x32_bf16 v[14:17], v[134:137], v[226:229], v[14:17]
	v_mfma_f32_16x16x32_bf16 v[10:13], v[152:155], v[226:229], v[10:13]
	v_mfma_f32_16x16x32_bf16 v[54:57], v[156:159], v[178:181], v[54:57]
	v_mfma_f32_16x16x32_bf16 v[50:53], v[170:173], v[178:181], v[50:53]
	v_mfma_f32_16x16x32_bf16 v[38:41], v[156:159], v[186:189], v[38:41]
	v_mfma_f32_16x16x32_bf16 v[34:37], v[170:173], v[186:189], v[34:37]
	v_mfma_f32_16x16x32_bf16 v[22:25], v[156:159], v[204:207], v[22:25]
	v_mfma_f32_16x16x32_bf16 v[18:21], v[170:173], v[204:207], v[18:21]
	v_mfma_f32_16x16x32_bf16 v[6:9], v[156:159], v[222:225], v[6:9]
	v_mfma_f32_16x16x32_bf16 v[2:5], v[170:173], v[222:225], v[2:5]
	v_mfma_f32_16x16x32_bf16 v[54:57], v[166:169], v[182:185], v[54:57]
	v_mfma_f32_16x16x32_bf16 v[50:53], v[174:177], v[182:185], v[50:53]
	v_mfma_f32_16x16x32_bf16 v[38:41], v[166:169], v[190:193], v[38:41]
	v_mfma_f32_16x16x32_bf16 v[34:37], v[174:177], v[190:193], v[34:37]
	v_mfma_f32_16x16x32_bf16 v[22:25], v[166:169], v[218:221], v[22:25]
	v_mfma_f32_16x16x32_bf16 v[18:21], v[174:177], v[218:221], v[18:21]
	v_mfma_f32_16x16x32_bf16 v[6:9], v[166:169], v[226:229], v[6:9]
	v_mfma_f32_16x16x32_bf16 v[2:5], v[174:177], v[226:229], v[2:5]
	s_barrier
	s_setprio 0
	s_add_i32 s63, s63, 2
	s_add_u32 s24, s24, 0x100
	s_addc_u32 s25, s25, 0
	s_add_u32 s27, s27, 0x100
	s_addc_u32 s62, s62, 0
	s_cmp_gt_u32 s63, 29
	s_cbranch_scc0 .LBB0_489
	s_and_b64 vcc, exec, s[18:19]
	s_cbranch_vccz .LBB0_492
	s_barrier

; #define PG8_STAGE(bufoff, gbase, voff) do { _Pragma("unroll") for (int _i = 0; _i < 2; ++_i) \
;         __builtin_amdgcn_global_load_lds((const unsigned*)((const char*)(gbase) + (voff)[_i]), (PG8_LAS unsigned*)(lds + (bufoff) + ldsw + _i * 8192), 16, 0, 0); } while (0)
; #define PG8_LDA(dst, b, h) do { _Pragma("unroll") for (int m = 0; m < 4; ++m) _Pragma("unroll") for (int k = 0; k < 2; ++k) dst[m][k] = *(const PG8_LAS bf16x8*)(lds + PG8_SA(b, h) + aoff + m * 2048 + k * 1024); } while (0)
; #define PG8_LDB(dst, b, h) do { _Pragma("unroll") for (int n = 0; n < 2; ++n) _Pragma("unroll") for (int k = 0; k < 2; ++k) dst[n][k] = *(const PG8_LAS bf16x8*)(lds + PG8_SB(b, h) + boff + n * 2048 + k * 1024); } while (0)
; #define PG8_MMA(ai, bj, At, Bt) do { __builtin_amdgcn_s_setprio(1); _Pragma("unroll") for (int m = 0; m < 4; ++m) _Pragma("unroll") for (int n = 0; n < 2; ++n) _Pragma("unroll") for (int k = 0; k < 2; ++k) \
;         acc[ai][bj][m][n] = __builtin_amdgcn_mfma_f32_16x16x32_bf16(Bt[n][k], At[m][k], acc[ai][bj][m][n], 0, 0, 0); __builtin_amdgcn_s_setprio(0); } while (0)
; #define PG8_WAIT_V(n) asm volatile("s_waitcnt vmcnt(" #n ")" ::: "memory")
; #define PG8_BAR __builtin_amdgcn_s_barrier()
; template <class Epi, class Sched, bool ALIGN_EPI = false, bool SP2 = false>
; __device__ __forceinline__ void gemm_phase(PG8_LAS unsigned char* lds, const Gemm g, const Sched& S, const Epi& E) {
;     ...
;         for (int t = 0; t < nt; t += 2) {
;             const bool last = (t == nt - 2);
;             const char* a1 = cA + (size_t)(t + 1) * kstep;
;             const char* a2 = last ? nA : cA + (size_t)(t + 2) * kstep; const char* b2 = last ? nB : cB + (size_t)(t + 2) * kstep;
;             const char* a3 = a2 + kstep; const char* b3 = b2 + kstep;
;             if (last && has_next) S.a_ready(nxt);
;             if constexpr (SP2) {
;             PG8_LDB(B0, 0, 0); PG8_LDB(B1, 0, 1); PG8_SCHED; PG8_LDA(At, 0, 0); PG8_STAGE(PG8_SA(1, 1), a1 + hstep, voffA);
;             PG8_WAIT_V(8); PG8_WAIT_L(0); PG8_BAR; PG8_MMA(0, 0, At, B0); PG8_MMA(0, 1, At, B1); PG8_BAR; PG8_SCHED;
;             PG8_LDA(At, 0, 1); PG8_STAGE(PG8_SB(0, 0), b2, voffB); PG8_STAGE(PG8_SB(0, 1), b2 + hstep, voffB); PG8_STAGE(PG8_SA(0, 0), a2, voffA);
;             PG8_WAIT_V(8); PG8_WAIT_L(0); PG8_BAR; PG8_MMA(1, 0, At, B0); PG8_MMA(1, 1, At, B1); PG8_BAR; PG8_SCHED;
.LBB0_516:
	s_add_u32 s20, s18, 0x100
	s_addc_u32 s21, s19, 0
	s_cmp_lg_u32 s38, 4
	s_cselect_b32 s22, s20, 0
	s_cselect_b32 s23, s21, 0
	s_add_u32 s24, s16, s22
	s_addc_u32 s25, s17, s23
	s_add_i32 s39, 0, 0x10000
	s_add_u32 s22, s14, s22
	s_addc_u32 s23, s15, s23
	s_add_i32 s40, 0, 0x14000
	v_add_u32_e32 v156, s39, v142
	v_add_u32_e32 v172, s40, v142
	ds_read_b128 v[144:147], v156
	ds_read_b128 v[148:151], v156 offset:1024
	ds_read_b128 v[152:155], v156 offset:2048
	ds_read_b128 v[156:159], v156 offset:3072
	ds_read_b128 v[160:163], v172
	ds_read_b128 v[164:167], v172 offset:1024
	ds_read_b128 v[168:171], v172 offset:2048
	ds_read_b128 v[172:175], v172 offset:3072
	v_lshl_add_u64 v[192:193], v[138:139], 0, s[18:19]
	s_add_i32 m0, s1, 0xc000
	ds_read_b128 v[176:179], v143
	ds_read_b128 v[180:183], v143 offset:1024
	ds_read_b128 v[184:187], v143 offset:2048
	ds_read_b128 v[188:191], v143 offset:3072
	ds_read_b128 v[204:207], v143 offset:4096
	ds_read_b128 v[220:223], v143 offset:5120
	ds_read_b128 v[224:227], v143 offset:6144
	ds_read_b128 v[228:231], v143 offset:7168
	global_load_lds_dwordx4 v[192:193], off
	v_lshl_add_u64 v[192:193], v[140:141], 0, s[18:19]
	s_add_i32 m0, s1, 0xe000
	s_nop 0
	global_load_lds_dwordx4 v[192:193], off
	s_waitcnt vmcnt(8)
	s_waitcnt lgkmcnt(0)
	s_setprio 1
	s_barrier
	v_mfma_f32_16x16x32_bf16 v[58:61], v[144:147], v[176:179], v[58:61]
	v_mfma_f32_16x16x32_bf16 v[62:65], v[152:155], v[176:179], v[62:65]
	v_mfma_f32_16x16x32_bf16 v[42:45], v[144:147], v[184:187], v[42:45]
	v_mfma_f32_16x16x32_bf16 v[46:49], v[152:155], v[184:187], v[46:49]
	v_mfma_f32_16x16x32_bf16 v[26:29], v[144:147], v[204:207], v[26:29]
	v_mfma_f32_16x16x32_bf16 v[30:33], v[152:155], v[204:207], v[30:33]
	v_mfma_f32_16x16x32_bf16 v[10:13], v[144:147], v[224:227], v[10:13]
	v_mfma_f32_16x16x32_bf16 v[14:17], v[152:155], v[224:227], v[14:17]
	v_mfma_f32_16x16x32_bf16 v[58:61], v[148:151], v[180:183], v[58:61]
	v_mfma_f32_16x16x32_bf16 v[62:65], v[156:159], v[180:183], v[62:65]
	v_mfma_f32_16x16x32_bf16 v[42:45], v[148:151], v[188:191], v[42:45]
	v_mfma_f32_16x16x32_bf16 v[46:49], v[156:159], v[188:191], v[46:49]
	v_mfma_f32_16x16x32_bf16 v[26:29], v[148:151], v[220:223], v[26:29]
	v_mfma_f32_16x16x32_bf16 v[30:33], v[156:159], v[220:223], v[30:33]
	v_mfma_f32_16x16x32_bf16 v[10:13], v[148:151], v[228:231], v[10:13]
	v_mfma_f32_16x16x32_bf16 v[14:17], v[156:159], v[228:231], v[14:17]
	v_mfma_f32_16x16x32_bf16 v[50:53], v[160:163], v[176:179], v[50:53]
	v_mfma_f32_16x16x32_bf16 v[54:57], v[168:171], v[176:179], v[54:57]
	v_mfma_f32_16x16x32_bf16 v[34:37], v[160:163], v[184:187], v[34:37]
	v_mfma_f32_16x16x32_bf16 v[38:41], v[168:171], v[184:187], v[38:41]
	v_mfma_f32_16x16x32_bf16 v[18:21], v[160:163], v[204:207], v[18:21]
	v_mfma_f32_16x16x32_bf16 v[22:25], v[168:171], v[204:207], v[22:25]
	v_mfma_f32_16x16x32_bf16 v[2:5], v[160:163], v[224:227], v[2:5]
	v_mfma_f32_16x16x32_bf16 v[6:9], v[168:171], v[224:227], v[6:9]
	v_mfma_f32_16x16x32_bf16 v[50:53], v[164:167], v[180:183], v[50:53]
	v_mfma_f32_16x16x32_bf16 v[54:57], v[172:175], v[180:183], v[54:57]
	v_mfma_f32_16x16x32_bf16 v[34:37], v[164:167], v[188:191], v[34:37]
	v_mfma_f32_16x16x32_bf16 v[38:41], v[172:175], v[188:191], v[38:41]
	v_mfma_f32_16x16x32_bf16 v[18:21], v[164:167], v[220:223], v[18:21]
	v_mfma_f32_16x16x32_bf16 v[22:25], v[172:175], v[220:223], v[22:25]
	v_mfma_f32_16x16x32_bf16 v[2:5], v[164:167], v[228:231], v[2:5]
	v_mfma_f32_16x16x32_bf16 v[6:9], v[172:175], v[228:231], v[6:9]
	s_barrier
	s_setprio 0
	s_add_i32 s18, s39, s3
	v_lshl_add_u64 v[192:193], s[22:23], 0, v[0:1]
	s_mov_b32 m0, s18
	ds_read_b128 v[176:179], v143 offset:16384
	ds_read_b128 v[180:183], v143 offset:17408
	ds_read_b128 v[184:187], v143 offset:18432
	ds_read_b128 v[188:191], v143 offset:19456
	ds_read_b128 v[204:207], v143 offset:20480
	ds_read_b128 v[220:223], v143 offset:21504
	ds_read_b128 v[224:227], v143 offset:22528
	ds_read_b128 v[228:231], v143 offset:23552
	global_load_lds_dwordx4 v[192:193], off
	s_add_i32 m0, s18, 0x2000
	s_add_u32 s18, s22, 0x80000
	v_lshl_add_u64 v[200:201], s[22:23], 0, v[136:137]
	s_addc_u32 s19, s23, 0
	s_add_i32 s39, s40, s3
	global_load_lds_dwordx4 v[200:201], off
	v_lshl_add_u64 v[202:203], s[18:19], 0, v[0:1]
	s_mov_b32 m0, s39
	v_lshl_add_u64 v[232:233], s[24:25], 0, v[134:135]
	global_load_lds_dwordx4 v[202:203], off
	v_lshl_add_u64 v[202:203], s[18:19], 0, v[136:137]
	s_add_i32 m0, s39, 0x2000
	s_nop 0
	global_load_lds_dwordx4 v[202:203], off
	v_lshl_add_u64 v[202:203], s[24:25], 0, v[132:133]
	s_mov_b32 m0, s1
	s_nop 0
	global_load_lds_dwordx4 v[202:203], off
	s_mov_b32 m0, s10
	s_nop 0
	global_load_lds_dwordx4 v[232:233], off
	s_waitcnt vmcnt(8)
	s_waitcnt lgkmcnt(0)
	s_setprio 1
	s_barrier
; #define PG8_STAGE(bufoff, gbase, voff) do { _Pragma("unroll") for (int _i = 0; _i < 2; ++_i) \
;         __builtin_amdgcn_global_load_lds((const unsigned*)((const char*)(gbase) + (voff)[_i]), (PG8_LAS unsigned*)(lds + (bufoff) + ldsw + _i * 8192), 16, 0, 0); } while (0)
; #define PG8_LDA(dst, b, h) do { _Pragma("unroll") for (int m = 0; m < 4; ++m) _Pragma("unroll") for (int k = 0; k < 2; ++k) dst[m][k] = *(const PG8_LAS bf16x8*)(lds + PG8_SA(b, h) + aoff + m * 2048 + k * 1024); } while (0)
; #define PG8_LDB(dst, b, h) do { _Pragma("unroll") for (int n = 0; n < 2; ++n) _Pragma("unroll") for (int k = 0; k < 2; ++k) dst[n][k] = *(const PG8_LAS bf16x8*)(lds + PG8_SB(b, h) + boff + n * 2048 + k * 1024); } while (0)
; #define PG8_MMA(ai, bj, At, Bt) do { __builtin_amdgcn_s_setprio(1); _Pragma("unroll") for (int m = 0; m < 4; ++m) _Pragma("unroll") for (int n = 0; n < 2; ++n) _Pragma("unroll") for (int k = 0; k < 2; ++k) \
;         acc[ai][bj][m][n] = __builtin_amdgcn_mfma_f32_16x16x32_bf16(Bt[n][k], At[m][k], acc[ai][bj][m][n], 0, 0, 0); __builtin_amdgcn_s_setprio(0); } while (0)
; #define PG8_WAIT_V(n) asm volatile("s_waitcnt vmcnt(" #n ")" ::: "memory")
; #define PG8_WAIT_L(n) asm volatile("s_waitcnt lgkmcnt(" #n ")" ::: "memory")
; #define PG8_BAR __builtin_amdgcn_s_barrier()
; #define PG8_SCHED __builtin_amdgcn_sched_barrier(0)
; template <class Epi, class Sched, bool ALIGN_EPI = false, bool SP2 = false>
; __device__ __forceinline__ void gemm_phase(PG8_LAS unsigned char* lds, const Gemm g, const Sched& S, const Epi& E) {
;     ...
;             PG8_WAIT_V(8); PG8_WAIT_L(0); PG8_BAR; PG8_MMA(1, 0, At, B0); PG8_MMA(1, 1, At, B1); PG8_BAR; PG8_SCHED;
;             PG8_LDB(B0, 1, 0); PG8_LDB(B1, 1, 1); PG8_SCHED; PG8_LDA(At, 1, 0); PG8_STAGE(PG8_SA(0, 1), a2 + hstep, voffA);
;             PG8_WAIT_V(8); PG8_WAIT_L(0); PG8_BAR; PG8_MMA(0, 0, At, B0); PG8_MMA(0, 1, At, B1); PG8_BAR; PG8_SCHED;
;             PG8_LDA(At, 1, 1); PG8_STAGE(PG8_SB(1, 0), b3, voffB); PG8_STAGE(PG8_SB(1, 1), b3 + hstep, voffB); PG8_STAGE(PG8_SA(1, 0), a3, voffA);
	v_mfma_f32_16x16x32_bf16 v[90:93], v[144:147], v[176:179], v[90:93]
	v_mfma_f32_16x16x32_bf16 v[94:97], v[152:155], v[176:179], v[94:97]
	v_mfma_f32_16x16x32_bf16 v[74:77], v[144:147], v[184:187], v[74:77]
	v_mfma_f32_16x16x32_bf16 v[78:81], v[152:155], v[184:187], v[78:81]
	v_mfma_f32_16x16x32_bf16 v[122:125], v[144:147], v[204:207], v[122:125]
	v_mfma_f32_16x16x32_bf16 v[126:129], v[152:155], v[204:207], v[126:129]
	v_mfma_f32_16x16x32_bf16 v[106:109], v[144:147], v[224:227], v[106:109]
	v_mfma_f32_16x16x32_bf16 v[110:113], v[152:155], v[224:227], v[110:113]
	v_mfma_f32_16x16x32_bf16 v[90:93], v[148:151], v[180:183], v[90:93]
	v_mfma_f32_16x16x32_bf16 v[94:97], v[156:159], v[180:183], v[94:97]
	v_mfma_f32_16x16x32_bf16 v[74:77], v[148:151], v[188:191], v[74:77]
	v_mfma_f32_16x16x32_bf16 v[78:81], v[156:159], v[188:191], v[78:81]
	v_mfma_f32_16x16x32_bf16 v[122:125], v[148:151], v[220:223], v[122:125]
	v_mfma_f32_16x16x32_bf16 v[126:129], v[156:159], v[220:223], v[126:129]
	v_mfma_f32_16x16x32_bf16 v[106:109], v[148:151], v[228:231], v[106:109]
	v_mfma_f32_16x16x32_bf16 v[110:113], v[156:159], v[228:231], v[110:113]
	v_mfma_f32_16x16x32_bf16 v[82:85], v[160:163], v[176:179], v[82:85]
	v_mfma_f32_16x16x32_bf16 v[86:89], v[168:171], v[176:179], v[86:89]
	v_mfma_f32_16x16x32_bf16 v[66:69], v[160:163], v[184:187], v[66:69]
	v_mfma_f32_16x16x32_bf16 v[70:73], v[168:171], v[184:187], v[70:73]
	v_mfma_f32_16x16x32_bf16 v[114:117], v[160:163], v[204:207], v[114:117]
	v_mfma_f32_16x16x32_bf16 v[118:121], v[168:171], v[204:207], v[118:121]
	v_mfma_f32_16x16x32_bf16 v[102:105], v[160:163], v[224:227], v[102:105]
	v_mfma_f32_16x16x32_bf16 v[98:101], v[168:171], v[224:227], v[98:101]
	v_mfma_f32_16x16x32_bf16 v[82:85], v[164:167], v[180:183], v[82:85]
	v_mfma_f32_16x16x32_bf16 v[86:89], v[172:175], v[180:183], v[86:89]
	v_mfma_f32_16x16x32_bf16 v[66:69], v[164:167], v[188:191], v[66:69]
	v_mfma_f32_16x16x32_bf16 v[70:73], v[172:175], v[188:191], v[70:73]
	v_mfma_f32_16x16x32_bf16 v[114:117], v[164:167], v[220:223], v[114:117]
	v_mfma_f32_16x16x32_bf16 v[118:121], v[172:175], v[220:223], v[118:121]
	v_mfma_f32_16x16x32_bf16 v[102:105], v[164:167], v[228:231], v[102:105]
	v_mfma_f32_16x16x32_bf16 v[98:101], v[172:175], v[228:231], v[98:101]
	s_barrier
	s_setprio 0
	s_add_i32 s39, 0, 0x18000
	s_add_i32 s40, 0, 0x1c000
	v_add_u32_e32 v156, s39, v142
	v_add_u32_e32 v172, s40, v142
	ds_read_b128 v[144:147], v156
	ds_read_b128 v[148:151], v156 offset:1024
	ds_read_b128 v[152:155], v156 offset:2048
	ds_read_b128 v[156:159], v156 offset:3072
	ds_read_b128 v[160:163], v172
	ds_read_b128 v[164:167], v172 offset:1024
	ds_read_b128 v[168:171], v172 offset:2048
	ds_read_b128 v[172:175], v172 offset:3072
	s_add_u32 s18, s24, 0x80000
	s_addc_u32 s19, s25, 0
	s_mov_b32 m0, s11
	v_lshl_add_u64 v[234:235], s[18:19], 0, v[132:133]
	ds_read_b128 v[176:179], v143 offset:32768
	ds_read_b128 v[180:183], v143 offset:33792
	ds_read_b128 v[184:187], v143 offset:34816
	ds_read_b128 v[188:191], v143 offset:35840
	ds_read_b128 v[204:207], v143 offset:36864
	ds_read_b128 v[220:223], v143 offset:37888
	ds_read_b128 v[224:227], v143 offset:38912
	ds_read_b128 v[228:231], v143 offset:39936
	global_load_lds_dwordx4 v[234:235], off
	v_lshl_add_u64 v[234:235], s[18:19], 0, v[134:135]
	s_mov_b32 m0, s27
	s_nop 0
	global_load_lds_dwordx4 v[234:235], off
	s_waitcnt vmcnt(8)
	s_waitcnt lgkmcnt(0)
	s_setprio 1
	s_barrier
	v_mfma_f32_16x16x32_bf16 v[58:61], v[144:147], v[176:179], v[58:61]
	v_mfma_f32_16x16x32_bf16 v[62:65], v[152:155], v[176:179], v[62:65]
	v_mfma_f32_16x16x32_bf16 v[42:45], v[144:147], v[184:187], v[42:45]
	v_mfma_f32_16x16x32_bf16 v[46:49], v[152:155], v[184:187], v[46:49]
	v_mfma_f32_16x16x32_bf16 v[26:29], v[144:147], v[204:207], v[26:29]
	v_mfma_f32_16x16x32_bf16 v[30:33], v[152:155], v[204:207], v[30:33]
	v_mfma_f32_16x16x32_bf16 v[10:13], v[144:147], v[224:227], v[10:13]
	v_mfma_f32_16x16x32_bf16 v[14:17], v[152:155], v[224:227], v[14:17]
	v_mfma_f32_16x16x32_bf16 v[58:61], v[148:151], v[180:183], v[58:61]
	v_mfma_f32_16x16x32_bf16 v[62:65], v[156:159], v[180:183], v[62:65]
	v_mfma_f32_16x16x32_bf16 v[42:45], v[148:151], v[188:191], v[42:45]
	v_mfma_f32_16x16x32_bf16 v[46:49], v[156:159], v[188:191], v[46:49]
	v_mfma_f32_16x16x32_bf16 v[26:29], v[148:151], v[220:223], v[26:29]
	v_mfma_f32_16x16x32_bf16 v[30:33], v[156:159], v[220:223], v[30:33]
	v_mfma_f32_16x16x32_bf16 v[10:13], v[148:151], v[228:231], v[10:13]
	v_mfma_f32_16x16x32_bf16 v[14:17], v[156:159], v[228:231], v[14:17]
	v_mfma_f32_16x16x32_bf16 v[50:53], v[160:163], v[176:179], v[50:53]
	v_mfma_f32_16x16x32_bf16 v[54:57], v[168:171], v[176:179], v[54:57]
	v_mfma_f32_16x16x32_bf16 v[34:37], v[160:163], v[184:187], v[34:37]
	v_mfma_f32_16x16x32_bf16 v[38:41], v[168:171], v[184:187], v[38:41]
	v_mfma_f32_16x16x32_bf16 v[18:21], v[160:163], v[204:207], v[18:21]
	v_mfma_f32_16x16x32_bf16 v[22:25], v[168:171], v[204:207], v[22:25]
	v_mfma_f32_16x16x32_bf16 v[2:5], v[160:163], v[224:227], v[2:5]
	v_mfma_f32_16x16x32_bf16 v[6:9], v[168:171], v[224:227], v[6:9]
	v_mfma_f32_16x16x32_bf16 v[50:53], v[164:167], v[180:183], v[50:53]
	v_mfma_f32_16x16x32_bf16 v[54:57], v[172:175], v[180:183], v[54:57]
	v_mfma_f32_16x16x32_bf16 v[34:37], v[164:167], v[188:191], v[34:37]
	v_mfma_f32_16x16x32_bf16 v[38:41], v[172:175], v[188:191], v[38:41]
	v_mfma_f32_16x16x32_bf16 v[18:21], v[164:167], v[220:223], v[18:21]
	v_mfma_f32_16x16x32_bf16 v[22:25], v[172:175], v[220:223], v[22:25]
	v_mfma_f32_16x16x32_bf16 v[2:5], v[164:167], v[228:231], v[2:5]
	v_mfma_f32_16x16x32_bf16 v[6:9], v[172:175], v[228:231], v[6:9]
	s_barrier
; #define PG8_STAGE(bufoff, gbase, voff) do { _Pragma("unroll") for (int _i = 0; _i < 2; ++_i) \
;         __builtin_amdgcn_global_load_lds((const unsigned*)((const char*)(gbase) + (voff)[_i]), (PG8_LAS unsigned*)(lds + (bufoff) + ldsw + _i * 8192), 16, 0, 0); } while (0)
; #define PG8_LDA(dst, b, h) do { _Pragma("unroll") for (int m = 0; m < 4; ++m) _Pragma("unroll") for (int k = 0; k < 2; ++k) dst[m][k] = *(const PG8_LAS bf16x8*)(lds + PG8_SA(b, h) + aoff + m * 2048 + k * 1024); } while (0)
; #define PG8_MMA(ai, bj, At, Bt) do { __builtin_amdgcn_s_setprio(1); _Pragma("unroll") for (int m = 0; m < 4; ++m) _Pragma("unroll") for (int n = 0; n < 2; ++n) _Pragma("unroll") for (int k = 0; k < 2; ++k) \
;         acc[ai][bj][m][n] = __builtin_amdgcn_mfma_f32_16x16x32_bf16(Bt[n][k], At[m][k], acc[ai][bj][m][n], 0, 0, 0); __builtin_amdgcn_s_setprio(0); } while (0)
; #define PG8_WAIT_V(n) asm volatile("s_waitcnt vmcnt(" #n ")" ::: "memory")
; #define PG8_WAIT_L(n) asm volatile("s_waitcnt lgkmcnt(" #n ")" ::: "memory")
; #define PG8_BAR __builtin_amdgcn_s_barrier()
; #define PG8_SCHED __builtin_amdgcn_sched_barrier(0)
; template <class Epi, class Sched, bool ALIGN_EPI = false, bool SP2 = false>
; __device__ __forceinline__ void gemm_phase(PG8_LAS unsigned char* lds, const Gemm g, const Sched& S, const Epi& E) {
;     ...
;             PG8_LDA(At, 1, 1); PG8_STAGE(PG8_SB(1, 0), b3, voffB); PG8_STAGE(PG8_SB(1, 1), b3 + hstep, voffB); PG8_STAGE(PG8_SA(1, 0), a3, voffA);
;             PG8_WAIT_V(8); PG8_WAIT_L(0); PG8_BAR; PG8_MMA(1, 0, At, B0); PG8_MMA(1, 1, At, B1); PG8_BAR; PG8_SCHED;
;     ...
;         if constexpr (ALIGN_EPI) { if (wr == 0) PG8_BAR; }
	s_setprio 0
	s_add_i32 s18, s39, s3
	v_lshl_add_u64 v[192:193], v[192:193], 0, s[56:57]
	s_mov_b32 m0, s18
	ds_read_b128 v[176:179], v143 offset:49152
	ds_read_b128 v[180:183], v143 offset:50176
	ds_read_b128 v[184:187], v143 offset:51200
	ds_read_b128 v[188:191], v143 offset:52224
	ds_read_b128 v[204:207], v143 offset:53248
	ds_read_b128 v[220:223], v143 offset:54272
	ds_read_b128 v[224:227], v143 offset:55296
	ds_read_b128 v[228:231], v143 offset:56320
	global_load_lds_dwordx4 v[192:193], off
	s_add_i32 m0, s18, 0x2000
	s_add_u32 s18, s22, 0x80080
	v_lshl_add_u64 v[192:193], v[200:201], 0, s[56:57]
	s_addc_u32 s19, s23, 0
	s_add_i32 s22, s40, s3
	global_load_lds_dwordx4 v[192:193], off
	v_lshl_add_u64 v[192:193], s[18:19], 0, v[0:1]
	s_mov_b32 m0, s22
	s_nop 0
	global_load_lds_dwordx4 v[192:193], off
	v_lshl_add_u64 v[192:193], s[18:19], 0, v[136:137]
	s_add_i32 m0, s22, 0x2000
	s_nop 0
	global_load_lds_dwordx4 v[192:193], off
	v_lshl_add_u64 v[192:193], v[202:203], 0, s[56:57]
	s_mov_b32 m0, s33
	s_nop 0
	global_load_lds_dwordx4 v[192:193], off
	v_lshl_add_u64 v[192:193], v[232:233], 0, s[56:57]
	s_mov_b32 m0, s37
	s_nop 0
	global_load_lds_dwordx4 v[192:193], off
	s_waitcnt vmcnt(8)
	s_waitcnt lgkmcnt(0)
	s_setprio 1
	s_barrier
	v_mfma_f32_16x16x32_bf16 v[90:93], v[144:147], v[176:179], v[90:93]
	v_mfma_f32_16x16x32_bf16 v[94:97], v[152:155], v[176:179], v[94:97]
	v_mfma_f32_16x16x32_bf16 v[74:77], v[144:147], v[184:187], v[74:77]
	v_mfma_f32_16x16x32_bf16 v[78:81], v[152:155], v[184:187], v[78:81]
	v_mfma_f32_16x16x32_bf16 v[122:125], v[144:147], v[204:207], v[122:125]
	v_mfma_f32_16x16x32_bf16 v[126:129], v[152:155], v[204:207], v[126:129]
	v_mfma_f32_16x16x32_bf16 v[106:109], v[144:147], v[224:227], v[106:109]
	v_mfma_f32_16x16x32_bf16 v[110:113], v[152:155], v[224:227], v[110:113]
	v_mfma_f32_16x16x32_bf16 v[90:93], v[148:151], v[180:183], v[90:93]
	v_mfma_f32_16x16x32_bf16 v[94:97], v[156:159], v[180:183], v[94:97]
	v_mfma_f32_16x16x32_bf16 v[74:77], v[148:151], v[188:191], v[74:77]
	v_mfma_f32_16x16x32_bf16 v[78:81], v[156:159], v[188:191], v[78:81]
	v_mfma_f32_16x16x32_bf16 v[122:125], v[148:151], v[220:223], v[122:125]
	v_mfma_f32_16x16x32_bf16 v[126:129], v[156:159], v[220:223], v[126:129]
	v_mfma_f32_16x16x32_bf16 v[106:109], v[148:151], v[228:231], v[106:109]
	v_mfma_f32_16x16x32_bf16 v[110:113], v[156:159], v[228:231], v[110:113]
	v_mfma_f32_16x16x32_bf16 v[82:85], v[160:163], v[176:179], v[82:85]
	v_mfma_f32_16x16x32_bf16 v[86:89], v[168:171], v[176:179], v[86:89]
	v_mfma_f32_16x16x32_bf16 v[66:69], v[160:163], v[184:187], v[66:69]
	v_mfma_f32_16x16x32_bf16 v[70:73], v[168:171], v[184:187], v[70:73]
	v_mfma_f32_16x16x32_bf16 v[114:117], v[160:163], v[204:207], v[114:117]
	v_mfma_f32_16x16x32_bf16 v[118:121], v[168:171], v[204:207], v[118:121]
	v_mfma_f32_16x16x32_bf16 v[102:105], v[160:163], v[224:227], v[102:105]
	v_mfma_f32_16x16x32_bf16 v[98:101], v[168:171], v[224:227], v[98:101]
	v_mfma_f32_16x16x32_bf16 v[82:85], v[164:167], v[180:183], v[82:85]
	v_mfma_f32_16x16x32_bf16 v[86:89], v[172:175], v[180:183], v[86:89]
	v_mfma_f32_16x16x32_bf16 v[66:69], v[164:167], v[188:191], v[66:69]
	v_mfma_f32_16x16x32_bf16 v[70:73], v[172:175], v[188:191], v[70:73]
	v_mfma_f32_16x16x32_bf16 v[114:117], v[164:167], v[220:223], v[114:117]
	v_mfma_f32_16x16x32_bf16 v[118:121], v[172:175], v[220:223], v[118:121]
	v_mfma_f32_16x16x32_bf16 v[102:105], v[164:167], v[228:231], v[102:105]
	v_mfma_f32_16x16x32_bf16 v[98:101], v[172:175], v[228:231], v[98:101]
	s_barrier
	s_setprio 0
	s_add_i32 s38, s38, 2
	s_cmp_gt_u32 s38, 5
	s_mov_b64 s[18:19], s[20:21]
	s_cbranch_scc0 .LBB0_516
	s_cmpk_lt_u32 s2, 0x100
	s_cbranch_scc0 .LBB0_519
	s_barrier

; #define PG8_STAGE(bufoff, gbase, voff) do { _Pragma("unroll") for (int _i = 0; _i < 2; ++_i) \
;         __builtin_amdgcn_global_load_lds((const unsigned*)((const char*)(gbase) + (voff)[_i]), (PG8_LAS unsigned*)(lds + (bufoff) + ldsw + _i * 8192), 16, 0, 0); } while (0)
; #define PG8_LDA(dst, b, h) do { _Pragma("unroll") for (int m = 0; m < 4; ++m) _Pragma("unroll") for (int k = 0; k < 2; ++k) dst[m][k] = *(const PG8_LAS bf16x8*)(lds + PG8_SA(b, h) + aoff + m * 2048 + k * 1024); } while (0)
; #define PG8_LDB(dst, b, h) do { _Pragma("unroll") for (int n = 0; n < 2; ++n) _Pragma("unroll") for (int k = 0; k < 2; ++k) dst[n][k] = *(const PG8_LAS bf16x8*)(lds + PG8_SB(b, h) + boff + n * 2048 + k * 1024); } while (0)
; #define PG8_MMA(ai, bj, At, Bt) do { __builtin_amdgcn_s_setprio(1); _Pragma("unroll") for (int m = 0; m < 4; ++m) _Pragma("unroll") for (int n = 0; n < 2; ++n) _Pragma("unroll") for (int k = 0; k < 2; ++k) \
;         acc[ai][bj][m][n] = __builtin_amdgcn_mfma_f32_16x16x32_bf16(Bt[n][k], At[m][k], acc[ai][bj][m][n], 0, 0, 0); __builtin_amdgcn_s_setprio(0); } while (0)
; #define PG8_WAIT_V(n) asm volatile("s_waitcnt vmcnt(" #n ")" ::: "memory")
; #define PG8_BAR __builtin_amdgcn_s_barrier()
; template <class Epi, class Sched, bool ALIGN_EPI = false, bool SP2 = false>
; __device__ __forceinline__ void gemm_phase(PG8_LAS unsigned char* lds, const Gemm g, const Sched& S, const Epi& E) {
;     ...
;         for (int t = 0; t < nt; t += 2) {
;             const bool last = (t == nt - 2);
;             const char* a1 = cA + (size_t)(t + 1) * kstep;
;             const char* a2 = last ? nA : cA + (size_t)(t + 2) * kstep; const char* b2 = last ? nB : cB + (size_t)(t + 2) * kstep;
;             const char* a3 = a2 + kstep; const char* b3 = b2 + kstep;
;             if (last && has_next) S.a_ready(nxt);
;             if constexpr (SP2) {
;             PG8_LDB(B0, 0, 0); PG8_LDB(B1, 0, 1); PG8_SCHED; PG8_LDA(At, 0, 0); PG8_STAGE(PG8_SA(1, 1), a1 + hstep, voffA);
;             PG8_WAIT_V(8); PG8_WAIT_L(0); PG8_BAR; PG8_MMA(0, 0, At, B0); PG8_MMA(0, 1, At, B1); PG8_BAR; PG8_SCHED;
;             PG8_LDA(At, 0, 1); PG8_STAGE(PG8_SB(0, 0), b2, voffB); PG8_STAGE(PG8_SB(0, 1), b2 + hstep, voffB); PG8_STAGE(PG8_SA(0, 0), a2, voffA);
;             PG8_WAIT_V(8); PG8_WAIT_L(0); PG8_BAR; PG8_MMA(1, 0, At, B0); PG8_MMA(1, 1, At, B1); PG8_BAR; PG8_SCHED;
.LBB0_643:
	s_add_u32 s44, s24, 0xfff80080
	s_addc_u32 s45, s25, -1
	s_add_i32 s74, 0, 0x10000
	s_cmp_eq_u32 s51, 28
	s_cselect_b32 s49, s21, s45
	s_cselect_b32 s48, s20, s44
	v_add_u32_e32 v0, s74, v192
	s_cselect_b32 s45, s19, s47
	s_cselect_b32 s44, s26, s27
	s_add_i32 s73, 0, 0x14000
	ds_read_b128 v[130:133], v0
	ds_read_b128 v[134:137], v0 offset:1024
	ds_read_b128 v[138:141], v0 offset:2048
	ds_read_b128 v[142:145], v0 offset:3072
	v_add_u32_e32 v0, s73, v192
	ds_read_b128 v[146:149], v0
	ds_read_b128 v[150:153], v0 offset:1024
	ds_read_b128 v[168:171], v0 offset:2048
	ds_read_b128 v[172:175], v0 offset:3072
	v_lshl_add_u64 v[154:155], s[24:25], 0, v[164:165]
	s_add_i32 m0, s77, 0xc000
	ds_read_b128 v[176:179], v193
	ds_read_b128 v[180:183], v193 offset:1024
	ds_read_b128 v[186:189], v193 offset:2048
	ds_read_b128 v[204:207], v193 offset:3072
	ds_read_b128 v[218:221], v193 offset:4096
	ds_read_b128 v[222:225], v193 offset:5120
	ds_read_b128 v[226:229], v193 offset:6144
	ds_read_b128 v[230:233], v193 offset:7168
	global_load_lds_dwordx4 v[154:155], off
	v_lshl_add_u64 v[154:155], s[24:25], 0, v[166:167]
	s_add_i32 m0, s77, 0xe000
	s_nop 0
	global_load_lds_dwordx4 v[154:155], off
	s_waitcnt vmcnt(8)
	s_waitcnt lgkmcnt(0)
	s_setprio 1
	s_barrier
	v_mfma_f32_16x16x32_bf16 v[126:129], v[130:133], v[176:179], v[126:129]
	v_mfma_f32_16x16x32_bf16 v[122:125], v[138:141], v[176:179], v[122:125]
	v_mfma_f32_16x16x32_bf16 v[110:113], v[130:133], v[186:189], v[110:113]
	v_mfma_f32_16x16x32_bf16 v[106:109], v[138:141], v[186:189], v[106:109]
	v_mfma_f32_16x16x32_bf16 v[94:97], v[130:133], v[218:221], v[94:97]
	v_mfma_f32_16x16x32_bf16 v[90:93], v[138:141], v[218:221], v[90:93]
	v_mfma_f32_16x16x32_bf16 v[78:81], v[130:133], v[226:229], v[78:81]
	v_mfma_f32_16x16x32_bf16 v[74:77], v[138:141], v[226:229], v[74:77]
	v_mfma_f32_16x16x32_bf16 v[126:129], v[134:137], v[180:183], v[126:129]
	v_mfma_f32_16x16x32_bf16 v[122:125], v[142:145], v[180:183], v[122:125]
	v_mfma_f32_16x16x32_bf16 v[110:113], v[134:137], v[204:207], v[110:113]
	v_mfma_f32_16x16x32_bf16 v[106:109], v[142:145], v[204:207], v[106:109]
	v_mfma_f32_16x16x32_bf16 v[94:97], v[134:137], v[222:225], v[94:97]
	v_mfma_f32_16x16x32_bf16 v[90:93], v[142:145], v[222:225], v[90:93]
	v_mfma_f32_16x16x32_bf16 v[78:81], v[134:137], v[230:233], v[78:81]
	v_mfma_f32_16x16x32_bf16 v[74:77], v[142:145], v[230:233], v[74:77]
	v_mfma_f32_16x16x32_bf16 v[114:117], v[146:149], v[176:179], v[114:117]
	v_mfma_f32_16x16x32_bf16 v[118:121], v[168:171], v[176:179], v[118:121]
	v_mfma_f32_16x16x32_bf16 v[98:101], v[146:149], v[186:189], v[98:101]
	v_mfma_f32_16x16x32_bf16 v[102:105], v[168:171], v[186:189], v[102:105]
	v_mfma_f32_16x16x32_bf16 v[82:85], v[146:149], v[218:221], v[82:85]
	v_mfma_f32_16x16x32_bf16 v[86:89], v[168:171], v[218:221], v[86:89]
	v_mfma_f32_16x16x32_bf16 v[66:69], v[146:149], v[226:229], v[66:69]
	v_mfma_f32_16x16x32_bf16 v[70:73], v[168:171], v[226:229], v[70:73]
	v_mfma_f32_16x16x32_bf16 v[114:117], v[150:153], v[180:183], v[114:117]
	v_mfma_f32_16x16x32_bf16 v[118:121], v[172:175], v[180:183], v[118:121]
	v_mfma_f32_16x16x32_bf16 v[98:101], v[150:153], v[204:207], v[98:101]
	v_mfma_f32_16x16x32_bf16 v[102:105], v[172:175], v[204:207], v[102:105]
	v_mfma_f32_16x16x32_bf16 v[82:85], v[150:153], v[222:225], v[82:85]
	v_mfma_f32_16x16x32_bf16 v[86:89], v[172:175], v[222:225], v[86:89]
	v_mfma_f32_16x16x32_bf16 v[66:69], v[150:153], v[230:233], v[66:69]
	v_mfma_f32_16x16x32_bf16 v[70:73], v[172:175], v[230:233], v[70:73]
	s_barrier
	s_setprio 0
	s_add_i32 s74, s74, s76
	v_lshl_add_u64 v[154:155], s[44:45], 0, v[158:159]
	s_mov_b32 m0, s74
	ds_read_b128 v[176:179], v193 offset:16384
	ds_read_b128 v[180:183], v193 offset:17408
	ds_read_b128 v[186:189], v193 offset:18432
	ds_read_b128 v[204:207], v193 offset:19456
	ds_read_b128 v[218:221], v193 offset:20480
	ds_read_b128 v[222:225], v193 offset:21504
	ds_read_b128 v[226:229], v193 offset:22528
	ds_read_b128 v[230:233], v193 offset:23552
	global_load_lds_dwordx4 v[154:155], off
	s_add_i32 m0, s74, 0x2000
	s_add_u32 vcc_lo, s44, 0x80000
	v_lshl_add_u64 v[200:201], s[44:45], 0, v[162:163]
	s_addc_u32 vcc_hi, s45, 0
	s_add_i32 s73, s73, s76
	global_load_lds_dwordx4 v[200:201], off
	v_lshl_add_u64 v[202:203], vcc, 0, v[158:159]
	s_mov_b32 m0, s73
	v_lshl_add_u64 v[234:235], s[48:49], 0, v[160:161]
	global_load_lds_dwordx4 v[202:203], off
	v_lshl_add_u64 v[202:203], vcc, 0, v[162:163]
	s_add_i32 m0, s73, 0x2000
	s_nop 0
	global_load_lds_dwordx4 v[202:203], off
	v_lshl_add_u64 v[202:203], s[48:49], 0, v[156:157]
	s_mov_b32 m0, s77
	s_nop 0
	global_load_lds_dwordx4 v[202:203], off
	s_mov_b32 m0, s78
	s_nop 0
	global_load_lds_dwordx4 v[234:235], off
	s_waitcnt vmcnt(8)
	s_waitcnt lgkmcnt(0)
	s_setprio 1
	s_barrier
; #define PG8_STAGE(bufoff, gbase, voff) do { _Pragma("unroll") for (int _i = 0; _i < 2; ++_i) \
;         __builtin_amdgcn_global_load_lds((const unsigned*)((const char*)(gbase) + (voff)[_i]), (PG8_LAS unsigned*)(lds + (bufoff) + ldsw + _i * 8192), 16, 0, 0); } while (0)
; #define PG8_LDA(dst, b, h) do { _Pragma("unroll") for (int m = 0; m < 4; ++m) _Pragma("unroll") for (int k = 0; k < 2; ++k) dst[m][k] = *(const PG8_LAS bf16x8*)(lds + PG8_SA(b, h) + aoff + m * 2048 + k * 1024); } while (0)
; #define PG8_LDB(dst, b, h) do { _Pragma("unroll") for (int n = 0; n < 2; ++n) _Pragma("unroll") for (int k = 0; k < 2; ++k) dst[n][k] = *(const PG8_LAS bf16x8*)(lds + PG8_SB(b, h) + boff + n * 2048 + k * 1024); } while (0)
; #define PG8_MMA(ai, bj, At, Bt) do { __builtin_amdgcn_s_setprio(1); _Pragma("unroll") for (int m = 0; m < 4; ++m) _Pragma("unroll") for (int n = 0; n < 2; ++n) _Pragma("unroll") for (int k = 0; k < 2; ++k) \
;         acc[ai][bj][m][n] = __builtin_amdgcn_mfma_f32_16x16x32_bf16(Bt[n][k], At[m][k], acc[ai][bj][m][n], 0, 0, 0); __builtin_amdgcn_s_setprio(0); } while (0)
; #define PG8_WAIT_V(n) asm volatile("s_waitcnt vmcnt(" #n ")" ::: "memory")
; #define PG8_WAIT_L(n) asm volatile("s_waitcnt lgkmcnt(" #n ")" ::: "memory")
; #define PG8_BAR __builtin_amdgcn_s_barrier()
; #define PG8_SCHED __builtin_amdgcn_sched_barrier(0)
; template <class Epi, class Sched, bool ALIGN_EPI = false, bool SP2 = false>
; __device__ __forceinline__ void gemm_phase(PG8_LAS unsigned char* lds, const Gemm g, const Sched& S, const Epi& E) {
;     ...
;             PG8_WAIT_V(8); PG8_WAIT_L(0); PG8_BAR; PG8_MMA(1, 0, At, B0); PG8_MMA(1, 1, At, B1); PG8_BAR; PG8_SCHED;
;             PG8_LDB(B0, 1, 0); PG8_LDB(B1, 1, 1); PG8_SCHED; PG8_LDA(At, 1, 0); PG8_STAGE(PG8_SA(0, 1), a2 + hstep, voffA);
;             PG8_WAIT_V(8); PG8_WAIT_L(0); PG8_BAR; PG8_MMA(0, 0, At, B0); PG8_MMA(0, 1, At, B1); PG8_BAR; PG8_SCHED;
;             PG8_LDA(At, 1, 1); PG8_STAGE(PG8_SB(1, 0), b3, voffB); PG8_STAGE(PG8_SB(1, 1), b3 + hstep, voffB); PG8_STAGE(PG8_SA(1, 0), a3, voffA);
	v_mfma_f32_16x16x32_bf16 v[62:65], v[130:133], v[176:179], v[62:65]
	v_mfma_f32_16x16x32_bf16 v[58:61], v[138:141], v[176:179], v[58:61]
	v_mfma_f32_16x16x32_bf16 v[46:49], v[130:133], v[186:189], v[46:49]
	v_mfma_f32_16x16x32_bf16 v[42:45], v[138:141], v[186:189], v[42:45]
	v_mfma_f32_16x16x32_bf16 v[30:33], v[130:133], v[218:221], v[30:33]
	v_mfma_f32_16x16x32_bf16 v[26:29], v[138:141], v[218:221], v[26:29]
	v_mfma_f32_16x16x32_bf16 v[14:17], v[130:133], v[226:229], v[14:17]
	v_mfma_f32_16x16x32_bf16 v[10:13], v[138:141], v[226:229], v[10:13]
	v_mfma_f32_16x16x32_bf16 v[62:65], v[134:137], v[180:183], v[62:65]
	v_mfma_f32_16x16x32_bf16 v[58:61], v[142:145], v[180:183], v[58:61]
	v_mfma_f32_16x16x32_bf16 v[46:49], v[134:137], v[204:207], v[46:49]
	v_mfma_f32_16x16x32_bf16 v[42:45], v[142:145], v[204:207], v[42:45]
	v_mfma_f32_16x16x32_bf16 v[30:33], v[134:137], v[222:225], v[30:33]
	v_mfma_f32_16x16x32_bf16 v[26:29], v[142:145], v[222:225], v[26:29]
	v_mfma_f32_16x16x32_bf16 v[14:17], v[134:137], v[230:233], v[14:17]
	v_mfma_f32_16x16x32_bf16 v[10:13], v[142:145], v[230:233], v[10:13]
	v_mfma_f32_16x16x32_bf16 v[50:53], v[146:149], v[176:179], v[50:53]
	v_mfma_f32_16x16x32_bf16 v[54:57], v[168:171], v[176:179], v[54:57]
	v_mfma_f32_16x16x32_bf16 v[34:37], v[146:149], v[186:189], v[34:37]
	v_mfma_f32_16x16x32_bf16 v[38:41], v[168:171], v[186:189], v[38:41]
	v_mfma_f32_16x16x32_bf16 v[18:21], v[146:149], v[218:221], v[18:21]
	v_mfma_f32_16x16x32_bf16 v[22:25], v[168:171], v[218:221], v[22:25]
	v_mfma_f32_16x16x32_bf16 v[2:5], v[146:149], v[226:229], v[2:5]
	v_mfma_f32_16x16x32_bf16 v[6:9], v[168:171], v[226:229], v[6:9]
	v_mfma_f32_16x16x32_bf16 v[50:53], v[150:153], v[180:183], v[50:53]
	v_mfma_f32_16x16x32_bf16 v[54:57], v[172:175], v[180:183], v[54:57]
	v_mfma_f32_16x16x32_bf16 v[34:37], v[150:153], v[204:207], v[34:37]
	v_mfma_f32_16x16x32_bf16 v[38:41], v[172:175], v[204:207], v[38:41]
	v_mfma_f32_16x16x32_bf16 v[18:21], v[150:153], v[222:225], v[18:21]
	v_mfma_f32_16x16x32_bf16 v[22:25], v[172:175], v[222:225], v[22:25]
	v_mfma_f32_16x16x32_bf16 v[2:5], v[150:153], v[230:233], v[2:5]
	v_mfma_f32_16x16x32_bf16 v[6:9], v[172:175], v[230:233], v[6:9]
	s_barrier
	s_setprio 0
	s_add_i32 s73, 0, 0x18000
	v_add_u32_e32 v0, s73, v192
	s_add_i32 s74, 0, 0x1c000
	ds_read_b128 v[130:133], v0
	ds_read_b128 v[134:137], v0 offset:1024
	ds_read_b128 v[138:141], v0 offset:2048
	ds_read_b128 v[142:145], v0 offset:3072
	v_add_u32_e32 v0, s74, v192
	ds_read_b128 v[146:149], v0
	ds_read_b128 v[150:153], v0 offset:1024
	ds_read_b128 v[168:171], v0 offset:2048
	ds_read_b128 v[172:175], v0 offset:3072
	s_add_u32 s48, s48, 0x80000
	s_addc_u32 s49, s49, 0
	s_mov_b32 m0, s79
	v_lshl_add_u64 v[236:237], s[48:49], 0, v[156:157]
	ds_read_b128 v[176:179], v193 offset:32768
	ds_read_b128 v[180:183], v193 offset:33792
	ds_read_b128 v[186:189], v193 offset:34816
	ds_read_b128 v[204:207], v193 offset:35840
	ds_read_b128 v[218:221], v193 offset:36864
	ds_read_b128 v[222:225], v193 offset:37888
	ds_read_b128 v[226:229], v193 offset:38912
	ds_read_b128 v[230:233], v193 offset:39936
	global_load_lds_dwordx4 v[236:237], off
	v_lshl_add_u64 v[236:237], s[48:49], 0, v[160:161]
	s_mov_b32 m0, s80
	s_nop 0
	global_load_lds_dwordx4 v[236:237], off
	s_waitcnt vmcnt(8)
	s_waitcnt lgkmcnt(0)
	s_setprio 1
	s_barrier
	v_mfma_f32_16x16x32_bf16 v[126:129], v[130:133], v[176:179], v[126:129]
	v_mfma_f32_16x16x32_bf16 v[122:125], v[138:141], v[176:179], v[122:125]
	v_mfma_f32_16x16x32_bf16 v[110:113], v[130:133], v[186:189], v[110:113]
	v_mfma_f32_16x16x32_bf16 v[106:109], v[138:141], v[186:189], v[106:109]
	v_mfma_f32_16x16x32_bf16 v[94:97], v[130:133], v[218:221], v[94:97]
	v_mfma_f32_16x16x32_bf16 v[90:93], v[138:141], v[218:221], v[90:93]
	v_mfma_f32_16x16x32_bf16 v[78:81], v[130:133], v[226:229], v[78:81]
	v_mfma_f32_16x16x32_bf16 v[74:77], v[138:141], v[226:229], v[74:77]
	v_mfma_f32_16x16x32_bf16 v[126:129], v[134:137], v[180:183], v[126:129]
	v_mfma_f32_16x16x32_bf16 v[122:125], v[142:145], v[180:183], v[122:125]
	v_mfma_f32_16x16x32_bf16 v[110:113], v[134:137], v[204:207], v[110:113]
	v_mfma_f32_16x16x32_bf16 v[106:109], v[142:145], v[204:207], v[106:109]
	v_mfma_f32_16x16x32_bf16 v[94:97], v[134:137], v[222:225], v[94:97]
	v_mfma_f32_16x16x32_bf16 v[90:93], v[142:145], v[222:225], v[90:93]
	v_mfma_f32_16x16x32_bf16 v[78:81], v[134:137], v[230:233], v[78:81]
	v_mfma_f32_16x16x32_bf16 v[74:77], v[142:145], v[230:233], v[74:77]
	v_mfma_f32_16x16x32_bf16 v[114:117], v[146:149], v[176:179], v[114:117]
	v_mfma_f32_16x16x32_bf16 v[118:121], v[168:171], v[176:179], v[118:121]
	v_mfma_f32_16x16x32_bf16 v[98:101], v[146:149], v[186:189], v[98:101]
	v_mfma_f32_16x16x32_bf16 v[102:105], v[168:171], v[186:189], v[102:105]
	v_mfma_f32_16x16x32_bf16 v[82:85], v[146:149], v[218:221], v[82:85]
	v_mfma_f32_16x16x32_bf16 v[86:89], v[168:171], v[218:221], v[86:89]
	v_mfma_f32_16x16x32_bf16 v[66:69], v[146:149], v[226:229], v[66:69]
	v_mfma_f32_16x16x32_bf16 v[70:73], v[168:171], v[226:229], v[70:73]
	v_mfma_f32_16x16x32_bf16 v[114:117], v[150:153], v[180:183], v[114:117]
	v_mfma_f32_16x16x32_bf16 v[118:121], v[172:175], v[180:183], v[118:121]
	v_mfma_f32_16x16x32_bf16 v[98:101], v[150:153], v[204:207], v[98:101]
	v_mfma_f32_16x16x32_bf16 v[102:105], v[172:175], v[204:207], v[102:105]
	v_mfma_f32_16x16x32_bf16 v[82:85], v[150:153], v[222:225], v[82:85]
	v_mfma_f32_16x16x32_bf16 v[86:89], v[172:175], v[222:225], v[86:89]
	v_mfma_f32_16x16x32_bf16 v[66:69], v[150:153], v[230:233], v[66:69]
	v_mfma_f32_16x16x32_bf16 v[70:73], v[172:175], v[230:233], v[70:73]
	s_barrier
; #define PG8_STAGE(bufoff, gbase, voff) do { _Pragma("unroll") for (int _i = 0; _i < 2; ++_i) \
;         __builtin_amdgcn_global_load_lds((const unsigned*)((const char*)(gbase) + (voff)[_i]), (PG8_LAS unsigned*)(lds + (bufoff) + ldsw + _i * 8192), 16, 0, 0); } while (0)
; #define PG8_LDA(dst, b, h) do { _Pragma("unroll") for (int m = 0; m < 4; ++m) _Pragma("unroll") for (int k = 0; k < 2; ++k) dst[m][k] = *(const PG8_LAS bf16x8*)(lds + PG8_SA(b, h) + aoff + m * 2048 + k * 1024); } while (0)
; #define PG8_MMA(ai, bj, At, Bt) do { __builtin_amdgcn_s_setprio(1); _Pragma("unroll") for (int m = 0; m < 4; ++m) _Pragma("unroll") for (int n = 0; n < 2; ++n) _Pragma("unroll") for (int k = 0; k < 2; ++k) \
;         acc[ai][bj][m][n] = __builtin_amdgcn_mfma_f32_16x16x32_bf16(Bt[n][k], At[m][k], acc[ai][bj][m][n], 0, 0, 0); __builtin_amdgcn_s_setprio(0); } while (0)
; #define PG8_WAIT_V(n) asm volatile("s_waitcnt vmcnt(" #n ")" ::: "memory")
; #define PG8_WAIT_L(n) asm volatile("s_waitcnt lgkmcnt(" #n ")" ::: "memory")
; #define PG8_BAR __builtin_amdgcn_s_barrier()
; #define PG8_SCHED __builtin_amdgcn_sched_barrier(0)
; template <class Epi, class Sched, bool ALIGN_EPI = false, bool SP2 = false>
; __device__ __forceinline__ void gemm_phase(PG8_LAS unsigned char* lds, const Gemm g, const Sched& S, const Epi& E) {
;     ...
;             PG8_LDA(At, 1, 1); PG8_STAGE(PG8_SB(1, 0), b3, voffB); PG8_STAGE(PG8_SB(1, 1), b3 + hstep, voffB); PG8_STAGE(PG8_SA(1, 0), a3, voffA);
;             PG8_WAIT_V(8); PG8_WAIT_L(0); PG8_BAR; PG8_MMA(1, 0, At, B0); PG8_MMA(1, 1, At, B1); PG8_BAR; PG8_SCHED;
;     ...
;         if constexpr (ALIGN_EPI) { if (wr == 0) PG8_BAR; }
	s_setprio 0
	s_add_i32 s48, s73, s76
	v_lshl_add_u64 v[154:155], v[154:155], 0, s[56:57]
	s_mov_b32 m0, s48
	ds_read_b128 v[176:179], v193 offset:49152
	ds_read_b128 v[180:183], v193 offset:50176
	ds_read_b128 v[186:189], v193 offset:51200
	ds_read_b128 v[204:207], v193 offset:52224
	ds_read_b128 v[218:221], v193 offset:53248
	ds_read_b128 v[222:225], v193 offset:54272
	ds_read_b128 v[226:229], v193 offset:55296
	ds_read_b128 v[230:233], v193 offset:56320
	global_load_lds_dwordx4 v[154:155], off
	s_add_i32 m0, s48, 0x2000
	s_add_u32 s44, s44, 0x80080
	v_lshl_add_u64 v[154:155], v[200:201], 0, s[56:57]
	s_addc_u32 s45, s45, 0
	s_add_i32 s48, s74, s76
	global_load_lds_dwordx4 v[154:155], off
	v_lshl_add_u64 v[154:155], s[44:45], 0, v[158:159]
	s_mov_b32 m0, s48
	s_nop 0
	global_load_lds_dwordx4 v[154:155], off
	v_lshl_add_u64 v[154:155], s[44:45], 0, v[162:163]
	s_add_i32 m0, s48, 0x2000
	s_nop 0
	global_load_lds_dwordx4 v[154:155], off
	v_lshl_add_u64 v[154:155], v[202:203], 0, s[56:57]
	s_mov_b32 m0, s88
	s_nop 0
	global_load_lds_dwordx4 v[154:155], off
	v_lshl_add_u64 v[154:155], v[234:235], 0, s[56:57]
	s_mov_b32 m0, s37
	s_nop 0
	global_load_lds_dwordx4 v[154:155], off
	s_waitcnt vmcnt(8)
	s_waitcnt lgkmcnt(0)
	s_setprio 1
	s_barrier
	v_mfma_f32_16x16x32_bf16 v[62:65], v[130:133], v[176:179], v[62:65]
	v_mfma_f32_16x16x32_bf16 v[58:61], v[138:141], v[176:179], v[58:61]
	v_mfma_f32_16x16x32_bf16 v[46:49], v[130:133], v[186:189], v[46:49]
	v_mfma_f32_16x16x32_bf16 v[42:45], v[138:141], v[186:189], v[42:45]
	v_mfma_f32_16x16x32_bf16 v[30:33], v[130:133], v[218:221], v[30:33]
	v_mfma_f32_16x16x32_bf16 v[26:29], v[138:141], v[218:221], v[26:29]
	v_mfma_f32_16x16x32_bf16 v[14:17], v[130:133], v[226:229], v[14:17]
	v_mfma_f32_16x16x32_bf16 v[10:13], v[138:141], v[226:229], v[10:13]
	v_mfma_f32_16x16x32_bf16 v[62:65], v[134:137], v[180:183], v[62:65]
	v_mfma_f32_16x16x32_bf16 v[58:61], v[142:145], v[180:183], v[58:61]
	v_mfma_f32_16x16x32_bf16 v[46:49], v[134:137], v[204:207], v[46:49]
	v_mfma_f32_16x16x32_bf16 v[42:45], v[142:145], v[204:207], v[42:45]
	v_mfma_f32_16x16x32_bf16 v[30:33], v[134:137], v[222:225], v[30:33]
	v_mfma_f32_16x16x32_bf16 v[26:29], v[142:145], v[222:225], v[26:29]
	v_mfma_f32_16x16x32_bf16 v[14:17], v[134:137], v[230:233], v[14:17]
	v_mfma_f32_16x16x32_bf16 v[10:13], v[142:145], v[230:233], v[10:13]
	v_mfma_f32_16x16x32_bf16 v[50:53], v[146:149], v[176:179], v[50:53]
	v_mfma_f32_16x16x32_bf16 v[54:57], v[168:171], v[176:179], v[54:57]
	v_mfma_f32_16x16x32_bf16 v[34:37], v[146:149], v[186:189], v[34:37]
	v_mfma_f32_16x16x32_bf16 v[38:41], v[168:171], v[186:189], v[38:41]
	v_mfma_f32_16x16x32_bf16 v[18:21], v[146:149], v[218:221], v[18:21]
	v_mfma_f32_16x16x32_bf16 v[22:25], v[168:171], v[218:221], v[22:25]
	v_mfma_f32_16x16x32_bf16 v[2:5], v[146:149], v[226:229], v[2:5]
	v_mfma_f32_16x16x32_bf16 v[6:9], v[168:171], v[226:229], v[6:9]
	v_mfma_f32_16x16x32_bf16 v[50:53], v[150:153], v[180:183], v[50:53]
	v_mfma_f32_16x16x32_bf16 v[54:57], v[172:175], v[180:183], v[54:57]
	v_mfma_f32_16x16x32_bf16 v[34:37], v[150:153], v[204:207], v[34:37]
	v_mfma_f32_16x16x32_bf16 v[38:41], v[172:175], v[204:207], v[38:41]
	v_mfma_f32_16x16x32_bf16 v[18:21], v[150:153], v[222:225], v[18:21]
	v_mfma_f32_16x16x32_bf16 v[22:25], v[172:175], v[222:225], v[22:25]
	v_mfma_f32_16x16x32_bf16 v[2:5], v[150:153], v[230:233], v[2:5]
	v_mfma_f32_16x16x32_bf16 v[6:9], v[172:175], v[230:233], v[6:9]
	s_barrier
	s_setprio 0
	s_add_i32 s51, s51, 2
	s_add_u32 s24, s24, 0x100
	s_addc_u32 s25, s25, 0
	s_add_u32 s27, s27, 0x100
	s_addc_u32 s47, s47, 0
	s_cmp_gt_u32 s51, 29
	s_cbranch_scc0 .LBB0_643
	s_and_b64 vcc, exec, s[68:69]
	s_cbranch_vccz .LBB0_646
	s_barrier

; #define PG8_STAGE(bufoff, gbase, voff) do { _Pragma("unroll") for (int _i = 0; _i < 2; ++_i) \
;         __builtin_amdgcn_global_load_lds((const unsigned*)((const char*)(gbase) + (voff)[_i]), (PG8_LAS unsigned*)(lds + (bufoff) + ldsw + _i * 8192), 16, 0, 0); } while (0)
; #define PG8_LDA(dst, b, h) do { _Pragma("unroll") for (int m = 0; m < 4; ++m) _Pragma("unroll") for (int k = 0; k < 2; ++k) dst[m][k] = *(const PG8_LAS bf16x8*)(lds + PG8_SA(b, h) + aoff + m * 2048 + k * 1024); } while (0)
; #define PG8_LDB(dst, b, h) do { _Pragma("unroll") for (int n = 0; n < 2; ++n) _Pragma("unroll") for (int k = 0; k < 2; ++k) dst[n][k] = *(const PG8_LAS bf16x8*)(lds + PG8_SB(b, h) + boff + n * 2048 + k * 1024); } while (0)
; #define PG8_MMA(ai, bj, At, Bt) do { __builtin_amdgcn_s_setprio(1); _Pragma("unroll") for (int m = 0; m < 4; ++m) _Pragma("unroll") for (int n = 0; n < 2; ++n) _Pragma("unroll") for (int k = 0; k < 2; ++k) \
;         acc[ai][bj][m][n] = __builtin_amdgcn_mfma_f32_16x16x32_bf16(Bt[n][k], At[m][k], acc[ai][bj][m][n], 0, 0, 0); __builtin_amdgcn_s_setprio(0); } while (0)
; #define PG8_WAIT_V(n) asm volatile("s_waitcnt vmcnt(" #n ")" ::: "memory")
; #define PG8_BAR __builtin_amdgcn_s_barrier()
; template <class Epi, class Sched, bool ALIGN_EPI = false, bool SP2 = false>
; __device__ __forceinline__ void gemm_phase(PG8_LAS unsigned char* lds, const Gemm g, const Sched& S, const Epi& E) {
;     ...
;         for (int t = 0; t < nt; t += 2) {
;             const bool last = (t == nt - 2);
;             const char* a1 = cA + (size_t)(t + 1) * kstep;
;             const char* a2 = last ? nA : cA + (size_t)(t + 2) * kstep; const char* b2 = last ? nB : cB + (size_t)(t + 2) * kstep;
;             const char* a3 = a2 + kstep; const char* b3 = b2 + kstep;
;             if (last && has_next) S.a_ready(nxt);
;             if constexpr (SP2) {
;             PG8_LDB(B0, 0, 0); PG8_LDB(B1, 0, 1); PG8_SCHED; PG8_LDA(At, 0, 0); PG8_STAGE(PG8_SA(1, 1), a1 + hstep, voffA);
;             PG8_WAIT_V(8); PG8_WAIT_L(0); PG8_BAR; PG8_MMA(0, 0, At, B0); PG8_MMA(0, 1, At, B1); PG8_BAR; PG8_SCHED;
;             PG8_LDA(At, 0, 1); PG8_STAGE(PG8_SB(0, 0), b2, voffB); PG8_STAGE(PG8_SB(0, 1), b2 + hstep, voffB); PG8_STAGE(PG8_SA(0, 0), a2, voffA);
;             PG8_WAIT_V(8); PG8_WAIT_L(0); PG8_BAR; PG8_MMA(1, 0, At, B0); PG8_MMA(1, 1, At, B1); PG8_BAR; PG8_SCHED;
.LBB0_1000:
	s_add_u32 s24, s22, 0x100
	s_addc_u32 s25, s23, 0
	s_add_i32 s59, 0, 0x10000
	s_cmpk_eq_i32 s58, 0x54
	s_cselect_b32 s45, s19, s25
	s_cselect_b32 s44, s18, s24
	s_cselect_b32 s41, s21, s55
	s_cselect_b32 s40, s20, s54
	s_add_i32 s62, 0, 0x14000
	v_add_u32_e32 v152, s59, v163
	v_add_u32_e32 v160, s62, v163
	ds_read_b128 v[130:133], v152
	ds_read_b128 v[134:137], v152 offset:1024
	ds_read_b128 v[138:141], v152 offset:2048
	ds_read_b128 v[152:155], v152 offset:3072
	ds_read_b128 v[156:159], v160
	ds_read_b128 v[166:169], v160 offset:1024
	ds_read_b128 v[170:173], v160 offset:2048
	ds_read_b128 v[174:177], v160 offset:3072
	v_lshl_add_u64 v[160:161], s[22:23], 0, v[148:149]
	s_add_i32 m0, s2, 0xc000
	ds_read_b128 v[178:181], v165
	ds_read_b128 v[182:185], v165 offset:1024
	ds_read_b128 v[186:189], v165 offset:2048
	ds_read_b128 v[190:193], v165 offset:3072
	ds_read_b128 v[204:207], v165 offset:4096
	ds_read_b128 v[218:221], v165 offset:5120
	ds_read_b128 v[222:225], v165 offset:6144
	ds_read_b128 v[226:229], v165 offset:7168
	global_load_lds_dwordx4 v[160:161], off
	v_lshl_add_u64 v[160:161], s[22:23], 0, v[150:151]
	s_add_i32 m0, s2, 0xe000
	s_nop 0
	global_load_lds_dwordx4 v[160:161], off
	s_waitcnt vmcnt(8)
	s_waitcnt lgkmcnt(0)
	s_setprio 1
	s_barrier
	v_mfma_f32_16x16x32_bf16 v[126:129], v[130:133], v[178:181], v[126:129]
	v_mfma_f32_16x16x32_bf16 v[122:125], v[138:141], v[178:181], v[122:125]
	v_mfma_f32_16x16x32_bf16 v[110:113], v[130:133], v[186:189], v[110:113]
	v_mfma_f32_16x16x32_bf16 v[106:109], v[138:141], v[186:189], v[106:109]
	v_mfma_f32_16x16x32_bf16 v[94:97], v[130:133], v[204:207], v[94:97]
	v_mfma_f32_16x16x32_bf16 v[90:93], v[138:141], v[204:207], v[90:93]
	v_mfma_f32_16x16x32_bf16 v[78:81], v[130:133], v[222:225], v[78:81]
	v_mfma_f32_16x16x32_bf16 v[74:77], v[138:141], v[222:225], v[74:77]
	v_mfma_f32_16x16x32_bf16 v[126:129], v[134:137], v[182:185], v[126:129]
	v_mfma_f32_16x16x32_bf16 v[122:125], v[152:155], v[182:185], v[122:125]
	v_mfma_f32_16x16x32_bf16 v[110:113], v[134:137], v[190:193], v[110:113]
	v_mfma_f32_16x16x32_bf16 v[106:109], v[152:155], v[190:193], v[106:109]
	v_mfma_f32_16x16x32_bf16 v[94:97], v[134:137], v[218:221], v[94:97]
	v_mfma_f32_16x16x32_bf16 v[90:93], v[152:155], v[218:221], v[90:93]
	v_mfma_f32_16x16x32_bf16 v[78:81], v[134:137], v[226:229], v[78:81]
	v_mfma_f32_16x16x32_bf16 v[74:77], v[152:155], v[226:229], v[74:77]
	v_mfma_f32_16x16x32_bf16 v[118:121], v[156:159], v[178:181], v[118:121]
	v_mfma_f32_16x16x32_bf16 v[114:117], v[170:173], v[178:181], v[114:117]
	v_mfma_f32_16x16x32_bf16 v[102:105], v[156:159], v[186:189], v[102:105]
	v_mfma_f32_16x16x32_bf16 v[98:101], v[170:173], v[186:189], v[98:101]
	v_mfma_f32_16x16x32_bf16 v[86:89], v[156:159], v[204:207], v[86:89]
	v_mfma_f32_16x16x32_bf16 v[82:85], v[170:173], v[204:207], v[82:85]
	v_mfma_f32_16x16x32_bf16 v[70:73], v[156:159], v[222:225], v[70:73]
	v_mfma_f32_16x16x32_bf16 v[66:69], v[170:173], v[222:225], v[66:69]
	v_mfma_f32_16x16x32_bf16 v[118:121], v[166:169], v[182:185], v[118:121]
	v_mfma_f32_16x16x32_bf16 v[114:117], v[174:177], v[182:185], v[114:117]
	v_mfma_f32_16x16x32_bf16 v[102:105], v[166:169], v[190:193], v[102:105]
	v_mfma_f32_16x16x32_bf16 v[98:101], v[174:177], v[190:193], v[98:101]
	v_mfma_f32_16x16x32_bf16 v[86:89], v[166:169], v[218:221], v[86:89]
	v_mfma_f32_16x16x32_bf16 v[82:85], v[174:177], v[218:221], v[82:85]
	v_mfma_f32_16x16x32_bf16 v[70:73], v[166:169], v[226:229], v[70:73]
	v_mfma_f32_16x16x32_bf16 v[66:69], v[174:177], v[226:229], v[66:69]
	s_barrier
	s_setprio 0
	s_add_i32 s22, s59, s1
	v_lshl_add_u64 v[160:161], s[40:41], 0, v[0:1]
	s_mov_b32 m0, s22
	ds_read_b128 v[178:181], v165 offset:16384
	ds_read_b128 v[182:185], v165 offset:17408
	ds_read_b128 v[186:189], v165 offset:18432
	ds_read_b128 v[190:193], v165 offset:19456
	ds_read_b128 v[204:207], v165 offset:20480
	ds_read_b128 v[218:221], v165 offset:21504
	ds_read_b128 v[222:225], v165 offset:22528
	ds_read_b128 v[226:229], v165 offset:23552
	global_load_lds_dwordx4 v[160:161], off
	s_add_i32 m0, s22, 0x2000
	s_add_u32 s22, s40, 0x160000
	v_lshl_add_u64 v[200:201], s[40:41], 0, v[146:147]
	s_addc_u32 s23, s41, 0
	s_add_i32 s59, s62, s1
	global_load_lds_dwordx4 v[200:201], off
	v_lshl_add_u64 v[202:203], s[22:23], 0, v[0:1]
	s_mov_b32 m0, s59
	v_lshl_add_u64 v[230:231], s[44:45], 0, v[144:145]
	global_load_lds_dwordx4 v[202:203], off
	v_lshl_add_u64 v[202:203], s[22:23], 0, v[146:147]
	s_add_i32 m0, s59, 0x2000
	s_nop 0
	global_load_lds_dwordx4 v[202:203], off
	v_lshl_add_u64 v[202:203], s[44:45], 0, v[142:143]
	s_mov_b32 m0, s2
	s_nop 0
	global_load_lds_dwordx4 v[202:203], off
	s_mov_b32 m0, s3
	s_nop 0
	global_load_lds_dwordx4 v[230:231], off
	s_waitcnt vmcnt(8)
	s_waitcnt lgkmcnt(0)
	s_setprio 1
	s_barrier
; #define PG8_STAGE(bufoff, gbase, voff) do { _Pragma("unroll") for (int _i = 0; _i < 2; ++_i) \
;         __builtin_amdgcn_global_load_lds((const unsigned*)((const char*)(gbase) + (voff)[_i]), (PG8_LAS unsigned*)(lds + (bufoff) + ldsw + _i * 8192), 16, 0, 0); } while (0)
; #define PG8_LDA(dst, b, h) do { _Pragma("unroll") for (int m = 0; m < 4; ++m) _Pragma("unroll") for (int k = 0; k < 2; ++k) dst[m][k] = *(const PG8_LAS bf16x8*)(lds + PG8_SA(b, h) + aoff + m * 2048 + k * 1024); } while (0)
; #define PG8_LDB(dst, b, h) do { _Pragma("unroll") for (int n = 0; n < 2; ++n) _Pragma("unroll") for (int k = 0; k < 2; ++k) dst[n][k] = *(const PG8_LAS bf16x8*)(lds + PG8_SB(b, h) + boff + n * 2048 + k * 1024); } while (0)
; #define PG8_MMA(ai, bj, At, Bt) do { __builtin_amdgcn_s_setprio(1); _Pragma("unroll") for (int m = 0; m < 4; ++m) _Pragma("unroll") for (int n = 0; n < 2; ++n) _Pragma("unroll") for (int k = 0; k < 2; ++k) \
;         acc[ai][bj][m][n] = __builtin_amdgcn_mfma_f32_16x16x32_bf16(Bt[n][k], At[m][k], acc[ai][bj][m][n], 0, 0, 0); __builtin_amdgcn_s_setprio(0); } while (0)
; #define PG8_WAIT_V(n) asm volatile("s_waitcnt vmcnt(" #n ")" ::: "memory")
; #define PG8_WAIT_L(n) asm volatile("s_waitcnt lgkmcnt(" #n ")" ::: "memory")
; #define PG8_BAR __builtin_amdgcn_s_barrier()
; #define PG8_SCHED __builtin_amdgcn_sched_barrier(0)
; template <class Epi, class Sched, bool ALIGN_EPI = false, bool SP2 = false>
; __device__ __forceinline__ void gemm_phase(PG8_LAS unsigned char* lds, const Gemm g, const Sched& S, const Epi& E) {
;     ...
;             PG8_WAIT_V(8); PG8_WAIT_L(0); PG8_BAR; PG8_MMA(1, 0, At, B0); PG8_MMA(1, 1, At, B1); PG8_BAR; PG8_SCHED;
;             PG8_LDB(B0, 1, 0); PG8_LDB(B1, 1, 1); PG8_SCHED; PG8_LDA(At, 1, 0); PG8_STAGE(PG8_SA(0, 1), a2 + hstep, voffA);
;             PG8_WAIT_V(8); PG8_WAIT_L(0); PG8_BAR; PG8_MMA(0, 0, At, B0); PG8_MMA(0, 1, At, B1); PG8_BAR; PG8_SCHED;
;             PG8_LDA(At, 1, 1); PG8_STAGE(PG8_SB(1, 0), b3, voffB); PG8_STAGE(PG8_SB(1, 1), b3 + hstep, voffB); PG8_STAGE(PG8_SA(1, 0), a3, voffA);
	v_mfma_f32_16x16x32_bf16 v[62:65], v[130:133], v[178:181], v[62:65]
	v_mfma_f32_16x16x32_bf16 v[58:61], v[138:141], v[178:181], v[58:61]
	v_mfma_f32_16x16x32_bf16 v[46:49], v[130:133], v[186:189], v[46:49]
	v_mfma_f32_16x16x32_bf16 v[42:45], v[138:141], v[186:189], v[42:45]
	v_mfma_f32_16x16x32_bf16 v[30:33], v[130:133], v[204:207], v[30:33]
	v_mfma_f32_16x16x32_bf16 v[26:29], v[138:141], v[204:207], v[26:29]
	v_mfma_f32_16x16x32_bf16 v[14:17], v[130:133], v[222:225], v[14:17]
	v_mfma_f32_16x16x32_bf16 v[10:13], v[138:141], v[222:225], v[10:13]
	v_mfma_f32_16x16x32_bf16 v[62:65], v[134:137], v[182:185], v[62:65]
	v_mfma_f32_16x16x32_bf16 v[58:61], v[152:155], v[182:185], v[58:61]
	v_mfma_f32_16x16x32_bf16 v[46:49], v[134:137], v[190:193], v[46:49]
	v_mfma_f32_16x16x32_bf16 v[42:45], v[152:155], v[190:193], v[42:45]
	v_mfma_f32_16x16x32_bf16 v[30:33], v[134:137], v[218:221], v[30:33]
	v_mfma_f32_16x16x32_bf16 v[26:29], v[152:155], v[218:221], v[26:29]
	v_mfma_f32_16x16x32_bf16 v[14:17], v[134:137], v[226:229], v[14:17]
	v_mfma_f32_16x16x32_bf16 v[10:13], v[152:155], v[226:229], v[10:13]
	v_mfma_f32_16x16x32_bf16 v[54:57], v[156:159], v[178:181], v[54:57]
	v_mfma_f32_16x16x32_bf16 v[50:53], v[170:173], v[178:181], v[50:53]
	v_mfma_f32_16x16x32_bf16 v[38:41], v[156:159], v[186:189], v[38:41]
	v_mfma_f32_16x16x32_bf16 v[34:37], v[170:173], v[186:189], v[34:37]
	v_mfma_f32_16x16x32_bf16 v[22:25], v[156:159], v[204:207], v[22:25]
	v_mfma_f32_16x16x32_bf16 v[18:21], v[170:173], v[204:207], v[18:21]
	v_mfma_f32_16x16x32_bf16 v[6:9], v[156:159], v[222:225], v[6:9]
	v_mfma_f32_16x16x32_bf16 v[2:5], v[170:173], v[222:225], v[2:5]
	v_mfma_f32_16x16x32_bf16 v[54:57], v[166:169], v[182:185], v[54:57]
	v_mfma_f32_16x16x32_bf16 v[50:53], v[174:177], v[182:185], v[50:53]
	v_mfma_f32_16x16x32_bf16 v[38:41], v[166:169], v[190:193], v[38:41]
	v_mfma_f32_16x16x32_bf16 v[34:37], v[174:177], v[190:193], v[34:37]
	v_mfma_f32_16x16x32_bf16 v[22:25], v[166:169], v[218:221], v[22:25]
	v_mfma_f32_16x16x32_bf16 v[18:21], v[174:177], v[218:221], v[18:21]
	v_mfma_f32_16x16x32_bf16 v[6:9], v[166:169], v[226:229], v[6:9]
	v_mfma_f32_16x16x32_bf16 v[2:5], v[174:177], v[226:229], v[2:5]
	s_barrier
	s_setprio 0
	s_add_i32 s59, 0, 0x18000
	s_add_i32 s62, 0, 0x1c000
	v_add_u32_e32 v152, s59, v163
	v_add_u32_e32 v174, s62, v163
	ds_read_b128 v[130:133], v152
	ds_read_b128 v[134:137], v152 offset:1024
	ds_read_b128 v[138:141], v152 offset:2048
	ds_read_b128 v[152:155], v152 offset:3072
	ds_read_b128 v[156:159], v174
	ds_read_b128 v[166:169], v174 offset:1024
	ds_read_b128 v[170:173], v174 offset:2048
	ds_read_b128 v[174:177], v174 offset:3072
	s_add_u32 s22, s44, 0x160000
	s_addc_u32 s23, s45, 0
	s_mov_b32 m0, s10
	v_lshl_add_u64 v[232:233], s[22:23], 0, v[142:143]
	ds_read_b128 v[178:181], v165 offset:32768
	ds_read_b128 v[182:185], v165 offset:33792
	ds_read_b128 v[186:189], v165 offset:34816
	ds_read_b128 v[190:193], v165 offset:35840
	ds_read_b128 v[204:207], v165 offset:36864
	ds_read_b128 v[218:221], v165 offset:37888
	ds_read_b128 v[222:225], v165 offset:38912
	ds_read_b128 v[226:229], v165 offset:39936
	global_load_lds_dwordx4 v[232:233], off
	v_lshl_add_u64 v[232:233], s[22:23], 0, v[144:145]
	s_mov_b32 m0, s11
	s_nop 0
	global_load_lds_dwordx4 v[232:233], off
	s_waitcnt vmcnt(8)
	s_waitcnt lgkmcnt(0)
	s_setprio 1
	s_barrier
	v_mfma_f32_16x16x32_bf16 v[126:129], v[130:133], v[178:181], v[126:129]
	v_mfma_f32_16x16x32_bf16 v[122:125], v[138:141], v[178:181], v[122:125]
	v_mfma_f32_16x16x32_bf16 v[110:113], v[130:133], v[186:189], v[110:113]
	v_mfma_f32_16x16x32_bf16 v[106:109], v[138:141], v[186:189], v[106:109]
	v_mfma_f32_16x16x32_bf16 v[94:97], v[130:133], v[204:207], v[94:97]
	v_mfma_f32_16x16x32_bf16 v[90:93], v[138:141], v[204:207], v[90:93]
	v_mfma_f32_16x16x32_bf16 v[78:81], v[130:133], v[222:225], v[78:81]
	v_mfma_f32_16x16x32_bf16 v[74:77], v[138:141], v[222:225], v[74:77]
	v_mfma_f32_16x16x32_bf16 v[126:129], v[134:137], v[182:185], v[126:129]
	v_mfma_f32_16x16x32_bf16 v[122:125], v[152:155], v[182:185], v[122:125]
	v_mfma_f32_16x16x32_bf16 v[110:113], v[134:137], v[190:193], v[110:113]
	v_mfma_f32_16x16x32_bf16 v[106:109], v[152:155], v[190:193], v[106:109]
	v_mfma_f32_16x16x32_bf16 v[94:97], v[134:137], v[218:221], v[94:97]
	v_mfma_f32_16x16x32_bf16 v[90:93], v[152:155], v[218:221], v[90:93]
	v_mfma_f32_16x16x32_bf16 v[78:81], v[134:137], v[226:229], v[78:81]
	v_mfma_f32_16x16x32_bf16 v[74:77], v[152:155], v[226:229], v[74:77]
	v_mfma_f32_16x16x32_bf16 v[118:121], v[156:159], v[178:181], v[118:121]
	v_mfma_f32_16x16x32_bf16 v[114:117], v[170:173], v[178:181], v[114:117]
	v_mfma_f32_16x16x32_bf16 v[102:105], v[156:159], v[186:189], v[102:105]
	v_mfma_f32_16x16x32_bf16 v[98:101], v[170:173], v[186:189], v[98:101]
	v_mfma_f32_16x16x32_bf16 v[86:89], v[156:159], v[204:207], v[86:89]
	v_mfma_f32_16x16x32_bf16 v[82:85], v[170:173], v[204:207], v[82:85]
	v_mfma_f32_16x16x32_bf16 v[70:73], v[156:159], v[222:225], v[70:73]
	v_mfma_f32_16x16x32_bf16 v[66:69], v[170:173], v[222:225], v[66:69]
	v_mfma_f32_16x16x32_bf16 v[118:121], v[166:169], v[182:185], v[118:121]
	v_mfma_f32_16x16x32_bf16 v[114:117], v[174:177], v[182:185], v[114:117]
	v_mfma_f32_16x16x32_bf16 v[102:105], v[166:169], v[190:193], v[102:105]
	v_mfma_f32_16x16x32_bf16 v[98:101], v[174:177], v[190:193], v[98:101]
	v_mfma_f32_16x16x32_bf16 v[86:89], v[166:169], v[218:221], v[86:89]
	v_mfma_f32_16x16x32_bf16 v[82:85], v[174:177], v[218:221], v[82:85]
	v_mfma_f32_16x16x32_bf16 v[70:73], v[166:169], v[226:229], v[70:73]
	v_mfma_f32_16x16x32_bf16 v[66:69], v[174:177], v[226:229], v[66:69]
	s_barrier
; #define PG8_STAGE(bufoff, gbase, voff) do { _Pragma("unroll") for (int _i = 0; _i < 2; ++_i) \
;         __builtin_amdgcn_global_load_lds((const unsigned*)((const char*)(gbase) + (voff)[_i]), (PG8_LAS unsigned*)(lds + (bufoff) + ldsw + _i * 8192), 16, 0, 0); } while (0)
; #define PG8_LDA(dst, b, h) do { _Pragma("unroll") for (int m = 0; m < 4; ++m) _Pragma("unroll") for (int k = 0; k < 2; ++k) dst[m][k] = *(const PG8_LAS bf16x8*)(lds + PG8_SA(b, h) + aoff + m * 2048 + k * 1024); } while (0)
; #define PG8_MMA(ai, bj, At, Bt) do { __builtin_amdgcn_s_setprio(1); _Pragma("unroll") for (int m = 0; m < 4; ++m) _Pragma("unroll") for (int n = 0; n < 2; ++n) _Pragma("unroll") for (int k = 0; k < 2; ++k) \
;         acc[ai][bj][m][n] = __builtin_amdgcn_mfma_f32_16x16x32_bf16(Bt[n][k], At[m][k], acc[ai][bj][m][n], 0, 0, 0); __builtin_amdgcn_s_setprio(0); } while (0)
; #define PG8_WAIT_V(n) asm volatile("s_waitcnt vmcnt(" #n ")" ::: "memory")
; #define PG8_WAIT_L(n) asm volatile("s_waitcnt lgkmcnt(" #n ")" ::: "memory")
; #define PG8_BAR __builtin_amdgcn_s_barrier()
; #define PG8_SCHED __builtin_amdgcn_sched_barrier(0)
; template <class Epi, class Sched, bool ALIGN_EPI = false, bool SP2 = false>
; __device__ __forceinline__ void gemm_phase(PG8_LAS unsigned char* lds, const Gemm g, const Sched& S, const Epi& E) {
;     ...
;             PG8_LDA(At, 1, 1); PG8_STAGE(PG8_SB(1, 0), b3, voffB); PG8_STAGE(PG8_SB(1, 1), b3 + hstep, voffB); PG8_STAGE(PG8_SA(1, 0), a3, voffA);
;             PG8_WAIT_V(8); PG8_WAIT_L(0); PG8_BAR; PG8_MMA(1, 0, At, B0); PG8_MMA(1, 1, At, B1); PG8_BAR; PG8_SCHED;
;     ...
;         if constexpr (ALIGN_EPI) { if (wr == 0) PG8_BAR; }
	s_setprio 0
	s_add_i32 s22, s59, s1
	v_lshl_add_u64 v[160:161], v[160:161], 0, s[56:57]
	s_mov_b32 m0, s22
	ds_read_b128 v[178:181], v165 offset:49152
	ds_read_b128 v[182:185], v165 offset:50176
	ds_read_b128 v[186:189], v165 offset:51200
	ds_read_b128 v[190:193], v165 offset:52224
	ds_read_b128 v[204:207], v165 offset:53248
	ds_read_b128 v[218:221], v165 offset:54272
	ds_read_b128 v[222:225], v165 offset:55296
	ds_read_b128 v[226:229], v165 offset:56320
	global_load_lds_dwordx4 v[160:161], off
	s_add_i32 m0, s22, 0x2000
	s_add_u32 s22, s40, 0x160080
	v_lshl_add_u64 v[160:161], v[200:201], 0, s[56:57]
	s_addc_u32 s23, s41, 0
	s_add_i32 s40, s62, s1
	global_load_lds_dwordx4 v[160:161], off
	v_lshl_add_u64 v[160:161], s[22:23], 0, v[0:1]
	s_mov_b32 m0, s40
	s_nop 0
	global_load_lds_dwordx4 v[160:161], off
	v_lshl_add_u64 v[160:161], s[22:23], 0, v[146:147]
	s_add_i32 m0, s40, 0x2000
	s_nop 0
	global_load_lds_dwordx4 v[160:161], off
	v_lshl_add_u64 v[160:161], v[202:203], 0, s[56:57]
	s_mov_b32 m0, s37
	s_nop 0
	global_load_lds_dwordx4 v[160:161], off
	v_lshl_add_u64 v[160:161], v[230:231], 0, s[56:57]
	s_mov_b32 m0, s46
	s_nop 0
	global_load_lds_dwordx4 v[160:161], off
	s_waitcnt vmcnt(8)
	s_waitcnt lgkmcnt(0)
	s_setprio 1
	s_barrier
	v_mfma_f32_16x16x32_bf16 v[62:65], v[130:133], v[178:181], v[62:65]
	v_mfma_f32_16x16x32_bf16 v[58:61], v[138:141], v[178:181], v[58:61]
	v_mfma_f32_16x16x32_bf16 v[46:49], v[130:133], v[186:189], v[46:49]
	v_mfma_f32_16x16x32_bf16 v[42:45], v[138:141], v[186:189], v[42:45]
	v_mfma_f32_16x16x32_bf16 v[30:33], v[130:133], v[204:207], v[30:33]
	v_mfma_f32_16x16x32_bf16 v[26:29], v[138:141], v[204:207], v[26:29]
	v_mfma_f32_16x16x32_bf16 v[14:17], v[130:133], v[222:225], v[14:17]
	v_mfma_f32_16x16x32_bf16 v[10:13], v[138:141], v[222:225], v[10:13]
	v_mfma_f32_16x16x32_bf16 v[62:65], v[134:137], v[182:185], v[62:65]
	v_mfma_f32_16x16x32_bf16 v[58:61], v[152:155], v[182:185], v[58:61]
	v_mfma_f32_16x16x32_bf16 v[46:49], v[134:137], v[190:193], v[46:49]
	v_mfma_f32_16x16x32_bf16 v[42:45], v[152:155], v[190:193], v[42:45]
	v_mfma_f32_16x16x32_bf16 v[30:33], v[134:137], v[218:221], v[30:33]
	v_mfma_f32_16x16x32_bf16 v[26:29], v[152:155], v[218:221], v[26:29]
	v_mfma_f32_16x16x32_bf16 v[14:17], v[134:137], v[226:229], v[14:17]
	v_mfma_f32_16x16x32_bf16 v[10:13], v[152:155], v[226:229], v[10:13]
	v_mfma_f32_16x16x32_bf16 v[54:57], v[156:159], v[178:181], v[54:57]
	v_mfma_f32_16x16x32_bf16 v[50:53], v[170:173], v[178:181], v[50:53]
	v_mfma_f32_16x16x32_bf16 v[38:41], v[156:159], v[186:189], v[38:41]
	v_mfma_f32_16x16x32_bf16 v[34:37], v[170:173], v[186:189], v[34:37]
	v_mfma_f32_16x16x32_bf16 v[22:25], v[156:159], v[204:207], v[22:25]
	v_mfma_f32_16x16x32_bf16 v[18:21], v[170:173], v[204:207], v[18:21]
	v_mfma_f32_16x16x32_bf16 v[6:9], v[156:159], v[222:225], v[6:9]
	v_mfma_f32_16x16x32_bf16 v[2:5], v[170:173], v[222:225], v[2:5]
	v_mfma_f32_16x16x32_bf16 v[54:57], v[166:169], v[182:185], v[54:57]
	v_mfma_f32_16x16x32_bf16 v[50:53], v[174:177], v[182:185], v[50:53]
	v_mfma_f32_16x16x32_bf16 v[38:41], v[166:169], v[190:193], v[38:41]
	v_mfma_f32_16x16x32_bf16 v[34:37], v[174:177], v[190:193], v[34:37]
	v_mfma_f32_16x16x32_bf16 v[22:25], v[166:169], v[218:221], v[22:25]
	v_mfma_f32_16x16x32_bf16 v[18:21], v[174:177], v[218:221], v[18:21]
	v_mfma_f32_16x16x32_bf16 v[6:9], v[166:169], v[226:229], v[6:9]
	v_mfma_f32_16x16x32_bf16 v[2:5], v[174:177], v[226:229], v[2:5]
	s_barrier
	s_setprio 0
	s_add_i32 s58, s58, 2
	s_add_u32 s54, s54, 0x100
	s_addc_u32 s55, s55, 0
	s_cmpk_gt_u32 s58, 0x55
	s_mov_b64 s[22:23], s[24:25]
	s_cbranch_scc0 .LBB0_1000
	s_and_b64 vcc, exec, s[16:17]
	s_cbranch_vccz .LBB0_1003
	s_barrier

; #define PG8_STAGE(bufoff, gbase, voff) do { _Pragma("unroll") for (int _i = 0; _i < 2; ++_i) \
;         __builtin_amdgcn_global_load_lds((const unsigned*)((const char*)(gbase) + (voff)[_i]), (PG8_LAS unsigned*)(lds + (bufoff) + ldsw + _i * 8192), 16, 0, 0); } while (0)
; #define PG8_LDA(dst, b, h) do { _Pragma("unroll") for (int m = 0; m < 4; ++m) _Pragma("unroll") for (int k = 0; k < 2; ++k) dst[m][k] = *(const PG8_LAS bf16x8*)(lds + PG8_SA(b, h) + aoff + m * 2048 + k * 1024); } while (0)
; #define PG8_LDB(dst, b, h) do { _Pragma("unroll") for (int n = 0; n < 2; ++n) _Pragma("unroll") for (int k = 0; k < 2; ++k) dst[n][k] = *(const PG8_LAS bf16x8*)(lds + PG8_SB(b, h) + boff + n * 2048 + k * 1024); } while (0)
; #define PG8_MMA(ai, bj, At, Bt) do { __builtin_amdgcn_s_setprio(1); _Pragma("unroll") for (int m = 0; m < 4; ++m) _Pragma("unroll") for (int n = 0; n < 2; ++n) _Pragma("unroll") for (int k = 0; k < 2; ++k) \
;         acc[ai][bj][m][n] = __builtin_amdgcn_mfma_f32_16x16x32_bf16(Bt[n][k], At[m][k], acc[ai][bj][m][n], 0, 0, 0); __builtin_amdgcn_s_setprio(0); } while (0)
; #define PG8_WAIT_V(n) asm volatile("s_waitcnt vmcnt(" #n ")" ::: "memory")
; #define PG8_BAR __builtin_amdgcn_s_barrier()
; template <class Epi, class Sched, bool ALIGN_EPI = false, bool SP2 = false>
; __device__ __forceinline__ void gemm_phase(PG8_LAS unsigned char* lds, const Gemm g, const Sched& S, const Epi& E) {
;     ...
;         for (int t = 0; t < nt; t += 2) {
;             const bool last = (t == nt - 2);
;             const char* a1 = cA + (size_t)(t + 1) * kstep;
;             const char* a2 = last ? nA : cA + (size_t)(t + 2) * kstep; const char* b2 = last ? nB : cB + (size_t)(t + 2) * kstep;
;             const char* a3 = a2 + kstep; const char* b3 = b2 + kstep;
;             if (last && has_next) S.a_ready(nxt);
;             if constexpr (SP2) {
;             PG8_LDB(B0, 0, 0); PG8_LDB(B1, 0, 1); PG8_SCHED; PG8_LDA(At, 0, 0); PG8_STAGE(PG8_SA(1, 1), a1 + hstep, voffA);
;             PG8_WAIT_V(8); PG8_WAIT_L(0); PG8_BAR; PG8_MMA(0, 0, At, B0); PG8_MMA(0, 1, At, B1); PG8_BAR; PG8_SCHED;
;             PG8_LDA(At, 0, 1); PG8_STAGE(PG8_SB(0, 0), b2, voffB); PG8_STAGE(PG8_SB(0, 1), b2 + hstep, voffB); PG8_STAGE(PG8_SA(0, 0), a2, voffA);
;             PG8_WAIT_V(8); PG8_WAIT_L(0); PG8_BAR; PG8_MMA(1, 0, At, B0); PG8_MMA(1, 1, At, B1); PG8_BAR; PG8_SCHED;
.LBB0_1027:
	s_add_u32 s20, s18, 0x100
	s_addc_u32 s21, s19, 0
	s_cmp_lg_u32 s38, 18
	s_cselect_b32 s22, s20, 0
	s_cselect_b32 s23, s21, 0
	s_add_u32 s24, s16, s22
	s_addc_u32 s25, s17, s23
	s_add_i32 s39, 0, 0x10000
	s_add_u32 s22, s14, s22
	s_addc_u32 s23, s15, s23
	s_add_i32 s40, 0, 0x14000
	v_add_u32_e32 v156, s39, v142
	v_add_u32_e32 v172, s40, v142
	ds_read_b128 v[144:147], v156
	ds_read_b128 v[148:151], v156 offset:1024
	ds_read_b128 v[152:155], v156 offset:2048
	ds_read_b128 v[156:159], v156 offset:3072
	ds_read_b128 v[160:163], v172
	ds_read_b128 v[164:167], v172 offset:1024
	ds_read_b128 v[168:171], v172 offset:2048
	ds_read_b128 v[172:175], v172 offset:3072
	v_lshl_add_u64 v[192:193], v[138:139], 0, s[18:19]
	s_add_i32 m0, s3, 0xc000
	ds_read_b128 v[176:179], v143
	ds_read_b128 v[180:183], v143 offset:1024
	ds_read_b128 v[184:187], v143 offset:2048
	ds_read_b128 v[188:191], v143 offset:3072
	ds_read_b128 v[204:207], v143 offset:4096
	ds_read_b128 v[218:221], v143 offset:5120
	ds_read_b128 v[222:225], v143 offset:6144
	ds_read_b128 v[226:229], v143 offset:7168
	global_load_lds_dwordx4 v[192:193], off
	v_lshl_add_u64 v[192:193], v[140:141], 0, s[18:19]
	s_add_i32 m0, s3, 0xe000
	s_nop 0
	global_load_lds_dwordx4 v[192:193], off
	s_waitcnt vmcnt(8)
	s_waitcnt lgkmcnt(0)
	s_setprio 1
	s_barrier
	v_mfma_f32_16x16x32_bf16 v[58:61], v[144:147], v[176:179], v[58:61]
	v_mfma_f32_16x16x32_bf16 v[62:65], v[152:155], v[176:179], v[62:65]
	v_mfma_f32_16x16x32_bf16 v[42:45], v[144:147], v[184:187], v[42:45]
	v_mfma_f32_16x16x32_bf16 v[46:49], v[152:155], v[184:187], v[46:49]
	v_mfma_f32_16x16x32_bf16 v[26:29], v[144:147], v[204:207], v[26:29]
	v_mfma_f32_16x16x32_bf16 v[30:33], v[152:155], v[204:207], v[30:33]
	v_mfma_f32_16x16x32_bf16 v[10:13], v[144:147], v[222:225], v[10:13]
	v_mfma_f32_16x16x32_bf16 v[14:17], v[152:155], v[222:225], v[14:17]
	v_mfma_f32_16x16x32_bf16 v[58:61], v[148:151], v[180:183], v[58:61]
	v_mfma_f32_16x16x32_bf16 v[62:65], v[156:159], v[180:183], v[62:65]
	v_mfma_f32_16x16x32_bf16 v[42:45], v[148:151], v[188:191], v[42:45]
	v_mfma_f32_16x16x32_bf16 v[46:49], v[156:159], v[188:191], v[46:49]
	v_mfma_f32_16x16x32_bf16 v[26:29], v[148:151], v[218:221], v[26:29]
	v_mfma_f32_16x16x32_bf16 v[30:33], v[156:159], v[218:221], v[30:33]
	v_mfma_f32_16x16x32_bf16 v[10:13], v[148:151], v[226:229], v[10:13]
	v_mfma_f32_16x16x32_bf16 v[14:17], v[156:159], v[226:229], v[14:17]
	v_mfma_f32_16x16x32_bf16 v[50:53], v[160:163], v[176:179], v[50:53]
	v_mfma_f32_16x16x32_bf16 v[54:57], v[168:171], v[176:179], v[54:57]
	v_mfma_f32_16x16x32_bf16 v[34:37], v[160:163], v[184:187], v[34:37]
	v_mfma_f32_16x16x32_bf16 v[38:41], v[168:171], v[184:187], v[38:41]
	v_mfma_f32_16x16x32_bf16 v[18:21], v[160:163], v[204:207], v[18:21]
	v_mfma_f32_16x16x32_bf16 v[22:25], v[168:171], v[204:207], v[22:25]
	v_mfma_f32_16x16x32_bf16 v[2:5], v[160:163], v[222:225], v[2:5]
	v_mfma_f32_16x16x32_bf16 v[6:9], v[168:171], v[222:225], v[6:9]
	v_mfma_f32_16x16x32_bf16 v[50:53], v[164:167], v[180:183], v[50:53]
	v_mfma_f32_16x16x32_bf16 v[54:57], v[172:175], v[180:183], v[54:57]
	v_mfma_f32_16x16x32_bf16 v[34:37], v[164:167], v[188:191], v[34:37]
	v_mfma_f32_16x16x32_bf16 v[38:41], v[172:175], v[188:191], v[38:41]
	v_mfma_f32_16x16x32_bf16 v[18:21], v[164:167], v[218:221], v[18:21]
	v_mfma_f32_16x16x32_bf16 v[22:25], v[172:175], v[218:221], v[22:25]
	v_mfma_f32_16x16x32_bf16 v[2:5], v[164:167], v[226:229], v[2:5]
	v_mfma_f32_16x16x32_bf16 v[6:9], v[172:175], v[226:229], v[6:9]
	s_barrier
	s_setprio 0
	s_add_i32 s18, s39, s2
	v_lshl_add_u64 v[192:193], s[22:23], 0, v[0:1]
	s_mov_b32 m0, s18
	ds_read_b128 v[176:179], v143 offset:16384
	ds_read_b128 v[180:183], v143 offset:17408
	ds_read_b128 v[184:187], v143 offset:18432
	ds_read_b128 v[188:191], v143 offset:19456
	ds_read_b128 v[204:207], v143 offset:20480
	ds_read_b128 v[218:221], v143 offset:21504
	ds_read_b128 v[222:225], v143 offset:22528
	ds_read_b128 v[226:229], v143 offset:23552
	global_load_lds_dwordx4 v[192:193], off
	s_add_i32 m0, s18, 0x2000
	s_add_u32 s18, s22, 0x160000
	v_lshl_add_u64 v[200:201], s[22:23], 0, v[136:137]
	s_addc_u32 s19, s23, 0
	s_add_i32 s39, s40, s2
	global_load_lds_dwordx4 v[200:201], off
	v_lshl_add_u64 v[202:203], s[18:19], 0, v[0:1]
	s_mov_b32 m0, s39
	v_lshl_add_u64 v[230:231], s[24:25], 0, v[134:135]
	global_load_lds_dwordx4 v[202:203], off
	v_lshl_add_u64 v[202:203], s[18:19], 0, v[136:137]
	s_add_i32 m0, s39, 0x2000
	s_nop 0
	global_load_lds_dwordx4 v[202:203], off
	v_lshl_add_u64 v[202:203], s[24:25], 0, v[132:133]
	s_mov_b32 m0, s3
	s_nop 0
	global_load_lds_dwordx4 v[202:203], off
	s_mov_b32 m0, s10
	s_nop 0
	global_load_lds_dwordx4 v[230:231], off
	s_waitcnt vmcnt(8)
	s_waitcnt lgkmcnt(0)
	s_setprio 1
	s_barrier
; #define PG8_STAGE(bufoff, gbase, voff) do { _Pragma("unroll") for (int _i = 0; _i < 2; ++_i) \
;         __builtin_amdgcn_global_load_lds((const unsigned*)((const char*)(gbase) + (voff)[_i]), (PG8_LAS unsigned*)(lds + (bufoff) + ldsw + _i * 8192), 16, 0, 0); } while (0)
; #define PG8_LDA(dst, b, h) do { _Pragma("unroll") for (int m = 0; m < 4; ++m) _Pragma("unroll") for (int k = 0; k < 2; ++k) dst[m][k] = *(const PG8_LAS bf16x8*)(lds + PG8_SA(b, h) + aoff + m * 2048 + k * 1024); } while (0)
; #define PG8_LDB(dst, b, h) do { _Pragma("unroll") for (int n = 0; n < 2; ++n) _Pragma("unroll") for (int k = 0; k < 2; ++k) dst[n][k] = *(const PG8_LAS bf16x8*)(lds + PG8_SB(b, h) + boff + n * 2048 + k * 1024); } while (0)
; #define PG8_MMA(ai, bj, At, Bt) do { __builtin_amdgcn_s_setprio(1); _Pragma("unroll") for (int m = 0; m < 4; ++m) _Pragma("unroll") for (int n = 0; n < 2; ++n) _Pragma("unroll") for (int k = 0; k < 2; ++k) \
;         acc[ai][bj][m][n] = __builtin_amdgcn_mfma_f32_16x16x32_bf16(Bt[n][k], At[m][k], acc[ai][bj][m][n], 0, 0, 0); __builtin_amdgcn_s_setprio(0); } while (0)
; #define PG8_WAIT_V(n) asm volatile("s_waitcnt vmcnt(" #n ")" ::: "memory")
; #define PG8_WAIT_L(n) asm volatile("s_waitcnt lgkmcnt(" #n ")" ::: "memory")
; #define PG8_BAR __builtin_amdgcn_s_barrier()
; #define PG8_SCHED __builtin_amdgcn_sched_barrier(0)
; template <class Epi, class Sched, bool ALIGN_EPI = false, bool SP2 = false>
; __device__ __forceinline__ void gemm_phase(PG8_LAS unsigned char* lds, const Gemm g, const Sched& S, const Epi& E) {
;     ...
;             PG8_WAIT_V(8); PG8_WAIT_L(0); PG8_BAR; PG8_MMA(1, 0, At, B0); PG8_MMA(1, 1, At, B1); PG8_BAR; PG8_SCHED;
;             PG8_LDB(B0, 1, 0); PG8_LDB(B1, 1, 1); PG8_SCHED; PG8_LDA(At, 1, 0); PG8_STAGE(PG8_SA(0, 1), a2 + hstep, voffA);
;             PG8_WAIT_V(8); PG8_WAIT_L(0); PG8_BAR; PG8_MMA(0, 0, At, B0); PG8_MMA(0, 1, At, B1); PG8_BAR; PG8_SCHED;
;             PG8_LDA(At, 1, 1); PG8_STAGE(PG8_SB(1, 0), b3, voffB); PG8_STAGE(PG8_SB(1, 1), b3 + hstep, voffB); PG8_STAGE(PG8_SA(1, 0), a3, voffA);
	v_mfma_f32_16x16x32_bf16 v[90:93], v[144:147], v[176:179], v[90:93]
	v_mfma_f32_16x16x32_bf16 v[94:97], v[152:155], v[176:179], v[94:97]
	v_mfma_f32_16x16x32_bf16 v[74:77], v[144:147], v[184:187], v[74:77]
	v_mfma_f32_16x16x32_bf16 v[78:81], v[152:155], v[184:187], v[78:81]
	v_mfma_f32_16x16x32_bf16 v[122:125], v[144:147], v[204:207], v[122:125]
	v_mfma_f32_16x16x32_bf16 v[126:129], v[152:155], v[204:207], v[126:129]
	v_mfma_f32_16x16x32_bf16 v[106:109], v[144:147], v[222:225], v[106:109]
	v_mfma_f32_16x16x32_bf16 v[110:113], v[152:155], v[222:225], v[110:113]
	v_mfma_f32_16x16x32_bf16 v[90:93], v[148:151], v[180:183], v[90:93]
	v_mfma_f32_16x16x32_bf16 v[94:97], v[156:159], v[180:183], v[94:97]
	v_mfma_f32_16x16x32_bf16 v[74:77], v[148:151], v[188:191], v[74:77]
	v_mfma_f32_16x16x32_bf16 v[78:81], v[156:159], v[188:191], v[78:81]
	v_mfma_f32_16x16x32_bf16 v[122:125], v[148:151], v[218:221], v[122:125]
	v_mfma_f32_16x16x32_bf16 v[126:129], v[156:159], v[218:221], v[126:129]
	v_mfma_f32_16x16x32_bf16 v[106:109], v[148:151], v[226:229], v[106:109]
	v_mfma_f32_16x16x32_bf16 v[110:113], v[156:159], v[226:229], v[110:113]
	v_mfma_f32_16x16x32_bf16 v[82:85], v[160:163], v[176:179], v[82:85]
	v_mfma_f32_16x16x32_bf16 v[86:89], v[168:171], v[176:179], v[86:89]
	v_mfma_f32_16x16x32_bf16 v[66:69], v[160:163], v[184:187], v[66:69]
	v_mfma_f32_16x16x32_bf16 v[70:73], v[168:171], v[184:187], v[70:73]
	v_mfma_f32_16x16x32_bf16 v[114:117], v[160:163], v[204:207], v[114:117]
	v_mfma_f32_16x16x32_bf16 v[118:121], v[168:171], v[204:207], v[118:121]
	v_mfma_f32_16x16x32_bf16 v[102:105], v[160:163], v[222:225], v[102:105]
	v_mfma_f32_16x16x32_bf16 v[98:101], v[168:171], v[222:225], v[98:101]
	v_mfma_f32_16x16x32_bf16 v[82:85], v[164:167], v[180:183], v[82:85]
	v_mfma_f32_16x16x32_bf16 v[86:89], v[172:175], v[180:183], v[86:89]
	v_mfma_f32_16x16x32_bf16 v[66:69], v[164:167], v[188:191], v[66:69]
	v_mfma_f32_16x16x32_bf16 v[70:73], v[172:175], v[188:191], v[70:73]
	v_mfma_f32_16x16x32_bf16 v[114:117], v[164:167], v[218:221], v[114:117]
	v_mfma_f32_16x16x32_bf16 v[118:121], v[172:175], v[218:221], v[118:121]
	v_mfma_f32_16x16x32_bf16 v[102:105], v[164:167], v[226:229], v[102:105]
	v_mfma_f32_16x16x32_bf16 v[98:101], v[172:175], v[226:229], v[98:101]
	s_barrier
	s_setprio 0
	s_add_i32 s39, 0, 0x18000
	s_add_i32 s40, 0, 0x1c000
	v_add_u32_e32 v156, s39, v142
	v_add_u32_e32 v172, s40, v142
	ds_read_b128 v[144:147], v156
	ds_read_b128 v[148:151], v156 offset:1024
	ds_read_b128 v[152:155], v156 offset:2048
	ds_read_b128 v[156:159], v156 offset:3072
	ds_read_b128 v[160:163], v172
	ds_read_b128 v[164:167], v172 offset:1024
	ds_read_b128 v[168:171], v172 offset:2048
	ds_read_b128 v[172:175], v172 offset:3072
	s_add_u32 s18, s24, 0x160000
	s_addc_u32 s19, s25, 0
	s_mov_b32 m0, s11
	v_lshl_add_u64 v[232:233], s[18:19], 0, v[132:133]
	ds_read_b128 v[176:179], v143 offset:32768
	ds_read_b128 v[180:183], v143 offset:33792
	ds_read_b128 v[184:187], v143 offset:34816
	ds_read_b128 v[188:191], v143 offset:35840
	ds_read_b128 v[204:207], v143 offset:36864
	ds_read_b128 v[218:221], v143 offset:37888
	ds_read_b128 v[222:225], v143 offset:38912
	ds_read_b128 v[226:229], v143 offset:39936
	global_load_lds_dwordx4 v[232:233], off
	v_lshl_add_u64 v[232:233], s[18:19], 0, v[134:135]
	s_mov_b32 m0, s27
	s_nop 0
	global_load_lds_dwordx4 v[232:233], off
	s_waitcnt vmcnt(8)
	s_waitcnt lgkmcnt(0)
	s_setprio 1
	s_barrier
	v_mfma_f32_16x16x32_bf16 v[58:61], v[144:147], v[176:179], v[58:61]
	v_mfma_f32_16x16x32_bf16 v[62:65], v[152:155], v[176:179], v[62:65]
	v_mfma_f32_16x16x32_bf16 v[42:45], v[144:147], v[184:187], v[42:45]
	v_mfma_f32_16x16x32_bf16 v[46:49], v[152:155], v[184:187], v[46:49]
	v_mfma_f32_16x16x32_bf16 v[26:29], v[144:147], v[204:207], v[26:29]
	v_mfma_f32_16x16x32_bf16 v[30:33], v[152:155], v[204:207], v[30:33]
	v_mfma_f32_16x16x32_bf16 v[10:13], v[144:147], v[222:225], v[10:13]
	v_mfma_f32_16x16x32_bf16 v[14:17], v[152:155], v[222:225], v[14:17]
	v_mfma_f32_16x16x32_bf16 v[58:61], v[148:151], v[180:183], v[58:61]
	v_mfma_f32_16x16x32_bf16 v[62:65], v[156:159], v[180:183], v[62:65]
	v_mfma_f32_16x16x32_bf16 v[42:45], v[148:151], v[188:191], v[42:45]
	v_mfma_f32_16x16x32_bf16 v[46:49], v[156:159], v[188:191], v[46:49]
	v_mfma_f32_16x16x32_bf16 v[26:29], v[148:151], v[218:221], v[26:29]
	v_mfma_f32_16x16x32_bf16 v[30:33], v[156:159], v[218:221], v[30:33]
	v_mfma_f32_16x16x32_bf16 v[10:13], v[148:151], v[226:229], v[10:13]
	v_mfma_f32_16x16x32_bf16 v[14:17], v[156:159], v[226:229], v[14:17]
	v_mfma_f32_16x16x32_bf16 v[50:53], v[160:163], v[176:179], v[50:53]
	v_mfma_f32_16x16x32_bf16 v[54:57], v[168:171], v[176:179], v[54:57]
	v_mfma_f32_16x16x32_bf16 v[34:37], v[160:163], v[184:187], v[34:37]
	v_mfma_f32_16x16x32_bf16 v[38:41], v[168:171], v[184:187], v[38:41]
	v_mfma_f32_16x16x32_bf16 v[18:21], v[160:163], v[204:207], v[18:21]
	v_mfma_f32_16x16x32_bf16 v[22:25], v[168:171], v[204:207], v[22:25]
	v_mfma_f32_16x16x32_bf16 v[2:5], v[160:163], v[222:225], v[2:5]
	v_mfma_f32_16x16x32_bf16 v[6:9], v[168:171], v[222:225], v[6:9]
	v_mfma_f32_16x16x32_bf16 v[50:53], v[164:167], v[180:183], v[50:53]
	v_mfma_f32_16x16x32_bf16 v[54:57], v[172:175], v[180:183], v[54:57]
	v_mfma_f32_16x16x32_bf16 v[34:37], v[164:167], v[188:191], v[34:37]
	v_mfma_f32_16x16x32_bf16 v[38:41], v[172:175], v[188:191], v[38:41]
	v_mfma_f32_16x16x32_bf16 v[18:21], v[164:167], v[218:221], v[18:21]
	v_mfma_f32_16x16x32_bf16 v[22:25], v[172:175], v[218:221], v[22:25]
	v_mfma_f32_16x16x32_bf16 v[2:5], v[164:167], v[226:229], v[2:5]
	v_mfma_f32_16x16x32_bf16 v[6:9], v[172:175], v[226:229], v[6:9]
	s_barrier
; #define PG8_STAGE(bufoff, gbase, voff) do { _Pragma("unroll") for (int _i = 0; _i < 2; ++_i) \
;         __builtin_amdgcn_global_load_lds((const unsigned*)((const char*)(gbase) + (voff)[_i]), (PG8_LAS unsigned*)(lds + (bufoff) + ldsw + _i * 8192), 16, 0, 0); } while (0)
; #define PG8_LDA(dst, b, h) do { _Pragma("unroll") for (int m = 0; m < 4; ++m) _Pragma("unroll") for (int k = 0; k < 2; ++k) dst[m][k] = *(const PG8_LAS bf16x8*)(lds + PG8_SA(b, h) + aoff + m * 2048 + k * 1024); } while (0)
; #define PG8_MMA(ai, bj, At, Bt) do { __builtin_amdgcn_s_setprio(1); _Pragma("unroll") for (int m = 0; m < 4; ++m) _Pragma("unroll") for (int n = 0; n < 2; ++n) _Pragma("unroll") for (int k = 0; k < 2; ++k) \
;         acc[ai][bj][m][n] = __builtin_amdgcn_mfma_f32_16x16x32_bf16(Bt[n][k], At[m][k], acc[ai][bj][m][n], 0, 0, 0); __builtin_amdgcn_s_setprio(0); } while (0)
; #define PG8_WAIT_V(n) asm volatile("s_waitcnt vmcnt(" #n ")" ::: "memory")
; #define PG8_WAIT_L(n) asm volatile("s_waitcnt lgkmcnt(" #n ")" ::: "memory")
; #define PG8_BAR __builtin_amdgcn_s_barrier()
; #define PG8_SCHED __builtin_amdgcn_sched_barrier(0)
; template <class Epi, class Sched, bool ALIGN_EPI = false, bool SP2 = false>
; __device__ __forceinline__ void gemm_phase(PG8_LAS unsigned char* lds, const Gemm g, const Sched& S, const Epi& E) {
;     ...
;             PG8_LDA(At, 1, 1); PG8_STAGE(PG8_SB(1, 0), b3, voffB); PG8_STAGE(PG8_SB(1, 1), b3 + hstep, voffB); PG8_STAGE(PG8_SA(1, 0), a3, voffA);
;             PG8_WAIT_V(8); PG8_WAIT_L(0); PG8_BAR; PG8_MMA(1, 0, At, B0); PG8_MMA(1, 1, At, B1); PG8_BAR; PG8_SCHED;
;     ...
;         if constexpr (ALIGN_EPI) { if (wr == 0) PG8_BAR; }
	s_setprio 0
	s_add_i32 s18, s39, s2
	v_lshl_add_u64 v[192:193], v[192:193], 0, s[56:57]
	s_mov_b32 m0, s18
	ds_read_b128 v[176:179], v143 offset:49152
	ds_read_b128 v[180:183], v143 offset:50176
	ds_read_b128 v[184:187], v143 offset:51200
	ds_read_b128 v[188:191], v143 offset:52224
	ds_read_b128 v[204:207], v143 offset:53248
	ds_read_b128 v[218:221], v143 offset:54272
	ds_read_b128 v[222:225], v143 offset:55296
	ds_read_b128 v[226:229], v143 offset:56320
	global_load_lds_dwordx4 v[192:193], off
	s_add_i32 m0, s18, 0x2000
	s_add_u32 s18, s22, 0x160080
	v_lshl_add_u64 v[192:193], v[200:201], 0, s[56:57]
	s_addc_u32 s19, s23, 0
	s_add_i32 s22, s40, s2
	global_load_lds_dwordx4 v[192:193], off
	v_lshl_add_u64 v[192:193], s[18:19], 0, v[0:1]
	s_mov_b32 m0, s22
	s_nop 0
	global_load_lds_dwordx4 v[192:193], off
	v_lshl_add_u64 v[192:193], s[18:19], 0, v[136:137]
	s_add_i32 m0, s22, 0x2000
	s_nop 0
	global_load_lds_dwordx4 v[192:193], off
	v_lshl_add_u64 v[192:193], v[202:203], 0, s[56:57]
	s_mov_b32 m0, s33
	s_nop 0
	global_load_lds_dwordx4 v[192:193], off
	v_lshl_add_u64 v[192:193], v[230:231], 0, s[56:57]
	s_mov_b32 m0, s37
	s_nop 0
	global_load_lds_dwordx4 v[192:193], off
	s_waitcnt vmcnt(8)
	s_waitcnt lgkmcnt(0)
	s_setprio 1
	s_barrier
	v_mfma_f32_16x16x32_bf16 v[90:93], v[144:147], v[176:179], v[90:93]
	v_mfma_f32_16x16x32_bf16 v[94:97], v[152:155], v[176:179], v[94:97]
	v_mfma_f32_16x16x32_bf16 v[74:77], v[144:147], v[184:187], v[74:77]
	v_mfma_f32_16x16x32_bf16 v[78:81], v[152:155], v[184:187], v[78:81]
	v_mfma_f32_16x16x32_bf16 v[122:125], v[144:147], v[204:207], v[122:125]
	v_mfma_f32_16x16x32_bf16 v[126:129], v[152:155], v[204:207], v[126:129]
	v_mfma_f32_16x16x32_bf16 v[106:109], v[144:147], v[222:225], v[106:109]
	v_mfma_f32_16x16x32_bf16 v[110:113], v[152:155], v[222:225], v[110:113]
	v_mfma_f32_16x16x32_bf16 v[90:93], v[148:151], v[180:183], v[90:93]
	v_mfma_f32_16x16x32_bf16 v[94:97], v[156:159], v[180:183], v[94:97]
	v_mfma_f32_16x16x32_bf16 v[74:77], v[148:151], v[188:191], v[74:77]
	v_mfma_f32_16x16x32_bf16 v[78:81], v[156:159], v[188:191], v[78:81]
	v_mfma_f32_16x16x32_bf16 v[122:125], v[148:151], v[218:221], v[122:125]
	v_mfma_f32_16x16x32_bf16 v[126:129], v[156:159], v[218:221], v[126:129]
	v_mfma_f32_16x16x32_bf16 v[106:109], v[148:151], v[226:229], v[106:109]
	v_mfma_f32_16x16x32_bf16 v[110:113], v[156:159], v[226:229], v[110:113]
	v_mfma_f32_16x16x32_bf16 v[82:85], v[160:163], v[176:179], v[82:85]
	v_mfma_f32_16x16x32_bf16 v[86:89], v[168:171], v[176:179], v[86:89]
	v_mfma_f32_16x16x32_bf16 v[66:69], v[160:163], v[184:187], v[66:69]
	v_mfma_f32_16x16x32_bf16 v[70:73], v[168:171], v[184:187], v[70:73]
	v_mfma_f32_16x16x32_bf16 v[114:117], v[160:163], v[204:207], v[114:117]
	v_mfma_f32_16x16x32_bf16 v[118:121], v[168:171], v[204:207], v[118:121]
	v_mfma_f32_16x16x32_bf16 v[102:105], v[160:163], v[222:225], v[102:105]
	v_mfma_f32_16x16x32_bf16 v[98:101], v[168:171], v[222:225], v[98:101]
	v_mfma_f32_16x16x32_bf16 v[82:85], v[164:167], v[180:183], v[82:85]
	v_mfma_f32_16x16x32_bf16 v[86:89], v[172:175], v[180:183], v[86:89]
	v_mfma_f32_16x16x32_bf16 v[66:69], v[164:167], v[188:191], v[66:69]
	v_mfma_f32_16x16x32_bf16 v[70:73], v[172:175], v[188:191], v[70:73]
	v_mfma_f32_16x16x32_bf16 v[114:117], v[164:167], v[218:221], v[114:117]
	v_mfma_f32_16x16x32_bf16 v[118:121], v[172:175], v[218:221], v[118:121]
	v_mfma_f32_16x16x32_bf16 v[102:105], v[164:167], v[226:229], v[102:105]
	v_mfma_f32_16x16x32_bf16 v[98:101], v[172:175], v[226:229], v[98:101]
	s_barrier
	s_setprio 0
	s_add_i32 s38, s38, 2
	s_cmp_gt_u32 s38, 19
	s_mov_b64 s[18:19], s[20:21]
	s_cbranch_scc0 .LBB0_1027
	s_cmpk_lt_u32 s1, 0x100
	s_cbranch_scc0 .LBB0_1030
	s_barrier
